# GEMM k-loops: the redundant s_waitcnt lgkmcnt(0) after each phase's 's_barrier ; s_setprio 1' removed (24 sites; the same wait is issued just before the barrier), on top of v77
# baseline (speedup 1.0000x reference)
.LBB0_173:
	s_waitcnt lgkmcnt(0)
	ds_read_b128 v[148:151], v172
	ds_read_b128 v[152:155], v172 offset:1024
	ds_read_b128 v[156:159], v172 offset:2048
	ds_read_b128 v[160:163], v172 offset:3072
	ds_read_b128 v[178:181], v173
	ds_read_b128 v[182:185], v173 offset:1024
	ds_read_b128 v[186:189], v173 offset:2048
	ds_read_b128 v[190:193], v173 offset:3072
	s_add_u32 s7, s80, 0xfffc0080
	s_addc_u32 s24, s81, -1
	s_cmp_eq_u32 s6, 12
	s_cselect_b32 s85, s1, s24
	s_cselect_b32 s84, s75, s7
	s_cselect_b32 s83, s73, s33
	s_cselect_b32 s82, vcc_lo, vcc_hi
	v_lshl_add_u64 v[198:199], s[80:81], 0, v[140:141]
	s_add_i32 m0, s65, 0xc000
	ds_read_b128 v[194:197], v174
	ds_read_b128 v[202:205], v174 offset:1024
	ds_read_b128 v[210:213], v174 offset:2048
	ds_read_b128 v[214:217], v174 offset:3072
	ds_read_b128 v[218:221], v174 offset:4096
	ds_read_b128 v[222:225], v174 offset:5120
	ds_read_b128 v[226:229], v174 offset:6144
	ds_read_b128 v[230:233], v174 offset:7168
	global_load_lds_dwordx4 v[198:199], off
	v_lshl_add_u64 v[198:199], s[80:81], 0, v[142:143]
	s_add_i32 m0, s65, 0xe000
	s_nop 0
	global_load_lds_dwordx4 v[198:199], off
	s_waitcnt vmcnt(8)
	s_waitcnt lgkmcnt(0)
	s_barrier
	s_setprio 1
	v_mfma_f32_16x16x32_bf16 v[124:127], v[148:151], v[194:197], v[124:127]
	v_mfma_f32_16x16x32_bf16 v[120:123], v[156:159], v[194:197], v[120:123]
	v_mfma_f32_16x16x32_bf16 v[112:115], v[148:151], v[210:213], v[112:115]
	v_mfma_f32_16x16x32_bf16 v[104:107], v[156:159], v[210:213], v[104:107]
	v_mfma_f32_16x16x32_bf16 v[100:103], v[148:151], v[218:221], v[100:103]
	v_mfma_f32_16x16x32_bf16 v[92:95], v[156:159], v[218:221], v[92:95]
	v_mfma_f32_16x16x32_bf16 v[84:87], v[148:151], v[226:229], v[84:87]
	v_mfma_f32_16x16x32_bf16 v[76:79], v[156:159], v[226:229], v[76:79]
	v_mfma_f32_16x16x32_bf16 v[124:127], v[152:155], v[202:205], v[124:127]
	v_mfma_f32_16x16x32_bf16 v[120:123], v[160:163], v[202:205], v[120:123]
	v_mfma_f32_16x16x32_bf16 v[112:115], v[152:155], v[214:217], v[112:115]
	v_mfma_f32_16x16x32_bf16 v[104:107], v[160:163], v[214:217], v[104:107]
	v_mfma_f32_16x16x32_bf16 v[100:103], v[152:155], v[222:225], v[100:103]
	v_mfma_f32_16x16x32_bf16 v[92:95], v[160:163], v[222:225], v[92:95]
	v_mfma_f32_16x16x32_bf16 v[84:87], v[152:155], v[230:233], v[84:87]
	v_mfma_f32_16x16x32_bf16 v[76:79], v[160:163], v[230:233], v[76:79]
	v_mfma_f32_16x16x32_bf16 v[116:119], v[178:181], v[194:197], v[116:119]
	v_mfma_f32_16x16x32_bf16 v[108:111], v[186:189], v[194:197], v[108:111]
	v_mfma_f32_16x16x32_bf16 v[96:99], v[178:181], v[210:213], v[96:99]
	v_mfma_f32_16x16x32_bf16 v[88:91], v[186:189], v[210:213], v[88:91]
	v_mfma_f32_16x16x32_bf16 v[80:83], v[178:181], v[218:221], v[80:83]
	v_mfma_f32_16x16x32_bf16 v[72:75], v[186:189], v[218:221], v[72:75]
	v_mfma_f32_16x16x32_bf16 v[68:71], v[178:181], v[226:229], v[68:71]
	v_mfma_f32_16x16x32_bf16 v[64:67], v[186:189], v[226:229], v[64:67]
	v_mfma_f32_16x16x32_bf16 v[116:119], v[182:185], v[202:205], v[116:119]
	v_mfma_f32_16x16x32_bf16 v[108:111], v[190:193], v[202:205], v[108:111]
	v_mfma_f32_16x16x32_bf16 v[96:99], v[182:185], v[214:217], v[96:99]
	v_mfma_f32_16x16x32_bf16 v[88:91], v[190:193], v[214:217], v[88:91]
	v_mfma_f32_16x16x32_bf16 v[80:83], v[182:185], v[222:225], v[80:83]
	v_mfma_f32_16x16x32_bf16 v[72:75], v[190:193], v[222:225], v[72:75]
	v_mfma_f32_16x16x32_bf16 v[68:71], v[182:185], v[230:233], v[68:71]
	v_mfma_f32_16x16x32_bf16 v[64:67], v[190:193], v[230:233], v[64:67]
	s_setprio 0
	s_barrier
	s_add_i32 s7, s95, s13
	v_lshl_add_u64 v[198:199], s[82:83], 0, v[132:133]
	s_mov_b32 m0, s7
	ds_read_b128 v[194:197], v174 offset:16384
	ds_read_b128 v[202:205], v174 offset:17408
	ds_read_b128 v[210:213], v174 offset:18432
	ds_read_b128 v[214:217], v174 offset:19456
	ds_read_b128 v[218:221], v174 offset:20480
	ds_read_b128 v[222:225], v174 offset:21504
	ds_read_b128 v[226:229], v174 offset:22528
	ds_read_b128 v[230:233], v174 offset:23552
	global_load_lds_dwordx4 v[198:199], off
	s_add_i32 m0, s7, 0x2000
	s_add_u32 s24, s82, 0x40000
	v_lshl_add_u64 v[206:207], s[82:83], 0, v[136:137]
	s_addc_u32 s25, s83, 0
	s_add_i32 s7, s96, s13
	global_load_lds_dwordx4 v[206:207], off
	v_lshl_add_u64 v[234:235], s[24:25], 0, v[132:133]
	s_mov_b32 m0, s7
	v_lshl_add_u64 v[236:237], s[84:85], 0, v[134:135]
	global_load_lds_dwordx4 v[234:235], off
	v_lshl_add_u64 v[234:235], s[24:25], 0, v[136:137]
	s_add_i32 m0, s7, 0x2000
	s_nop 0
	global_load_lds_dwordx4 v[234:235], off
	s_waitcnt vmcnt(6)
	s_waitcnt lgkmcnt(0)
	s_barrier
	s_setprio 1
	v_mfma_f32_16x16x32_bf16 v[60:63], v[148:151], v[194:197], v[60:63]
	v_mfma_f32_16x16x32_bf16 v[56:59], v[156:159], v[194:197], v[56:59]
	v_mfma_f32_16x16x32_bf16 v[52:55], v[148:151], v[210:213], v[52:55]
	v_mfma_f32_16x16x32_bf16 v[44:47], v[156:159], v[210:213], v[44:47]
	v_mfma_f32_16x16x32_bf16 v[36:39], v[148:151], v[218:221], v[36:39]
	v_mfma_f32_16x16x32_bf16 v[28:31], v[156:159], v[218:221], v[28:31]
	v_mfma_f32_16x16x32_bf16 v[20:23], v[148:151], v[226:229], v[20:23]
	v_mfma_f32_16x16x32_bf16 v[12:15], v[156:159], v[226:229], v[12:15]
	v_mfma_f32_16x16x32_bf16 v[60:63], v[152:155], v[202:205], v[60:63]
	v_mfma_f32_16x16x32_bf16 v[56:59], v[160:163], v[202:205], v[56:59]
	v_mfma_f32_16x16x32_bf16 v[52:55], v[152:155], v[214:217], v[52:55]
	v_mfma_f32_16x16x32_bf16 v[44:47], v[160:163], v[214:217], v[44:47]
	v_mfma_f32_16x16x32_bf16 v[36:39], v[152:155], v[222:225], v[36:39]
	v_mfma_f32_16x16x32_bf16 v[28:31], v[160:163], v[222:225], v[28:31]
	v_mfma_f32_16x16x32_bf16 v[20:23], v[152:155], v[230:233], v[20:23]
	v_mfma_f32_16x16x32_bf16 v[12:15], v[160:163], v[230:233], v[12:15]
	v_mfma_f32_16x16x32_bf16 v[48:51], v[178:181], v[194:197], v[48:51]
	v_mfma_f32_16x16x32_bf16 v[40:43], v[186:189], v[194:197], v[40:43]
	v_mfma_f32_16x16x32_bf16 v[32:35], v[178:181], v[210:213], v[32:35]
	v_mfma_f32_16x16x32_bf16 v[24:27], v[186:189], v[210:213], v[24:27]
	v_mfma_f32_16x16x32_bf16 v[16:19], v[178:181], v[218:221], v[16:19]
	v_mfma_f32_16x16x32_bf16 v[8:11], v[186:189], v[218:221], v[8:11]
	v_mfma_f32_16x16x32_bf16 v[4:7], v[178:181], v[226:229], v[4:7]
	v_mfma_f32_16x16x32_bf16 v[0:3], v[186:189], v[226:229], v[0:3]
	v_mfma_f32_16x16x32_bf16 v[48:51], v[182:185], v[202:205], v[48:51]
	v_mfma_f32_16x16x32_bf16 v[40:43], v[190:193], v[202:205], v[40:43]
	v_mfma_f32_16x16x32_bf16 v[32:35], v[182:185], v[214:217], v[32:35]
	v_mfma_f32_16x16x32_bf16 v[24:27], v[190:193], v[214:217], v[24:27]
	v_mfma_f32_16x16x32_bf16 v[16:19], v[182:185], v[222:225], v[16:19]
	v_mfma_f32_16x16x32_bf16 v[8:11], v[190:193], v[222:225], v[8:11]
	v_mfma_f32_16x16x32_bf16 v[4:7], v[182:185], v[230:233], v[4:7]
	v_mfma_f32_16x16x32_bf16 v[0:3], v[190:193], v[230:233], v[0:3]
	s_setprio 0
	s_barrier
	s_add_i32 s7, 0, 0x18000
	v_add_u32_e32 v138, s7, v169
	s_add_i32 s86, 0, 0x1c000
	ds_read_b128 v[148:151], v138
	ds_read_b128 v[152:155], v138 offset:1024
	ds_read_b128 v[156:159], v138 offset:2048
	ds_read_b128 v[160:163], v138 offset:3072
	v_add_u32_e32 v138, s86, v169
	ds_read_b128 v[178:181], v138
	ds_read_b128 v[182:185], v138 offset:1024
	ds_read_b128 v[186:189], v138 offset:2048
	ds_read_b128 v[190:193], v138 offset:3072
	v_lshl_add_u64 v[234:235], s[84:85], 0, v[130:131]
	s_mov_b32 m0, s65
	s_nop 0
	global_load_lds_dwordx4 v[234:235], off
	s_mov_b32 m0, s69
	s_nop 0
	global_load_lds_dwordx4 v[236:237], off
	s_add_u32 s24, s84, 0x40000
	s_addc_u32 s25, s85, 0
	s_mov_b32 m0, s87
	v_lshl_add_u64 v[238:239], s[24:25], 0, v[130:131]
	ds_read_b128 v[194:197], v174 offset:32768
	ds_read_b128 v[202:205], v174 offset:33792
	ds_read_b128 v[210:213], v174 offset:34816
	ds_read_b128 v[214:217], v174 offset:35840
	ds_read_b128 v[218:221], v174 offset:36864
	ds_read_b128 v[222:225], v174 offset:37888
	ds_read_b128 v[226:229], v174 offset:38912
	ds_read_b128 v[230:233], v174 offset:39936
	global_load_lds_dwordx4 v[238:239], off
	v_lshl_add_u64 v[238:239], s[24:25], 0, v[134:135]
	s_mov_b32 m0, s88
	s_nop 0
	global_load_lds_dwordx4 v[238:239], off
	s_waitcnt vmcnt(8)
	s_waitcnt lgkmcnt(0)
	s_barrier
	s_setprio 1
	v_mfma_f32_16x16x32_bf16 v[124:127], v[148:151], v[194:197], v[124:127]
	v_mfma_f32_16x16x32_bf16 v[120:123], v[156:159], v[194:197], v[120:123]
	v_mfma_f32_16x16x32_bf16 v[112:115], v[148:151], v[210:213], v[112:115]
	v_mfma_f32_16x16x32_bf16 v[104:107], v[156:159], v[210:213], v[104:107]
	v_mfma_f32_16x16x32_bf16 v[100:103], v[148:151], v[218:221], v[100:103]
	v_mfma_f32_16x16x32_bf16 v[92:95], v[156:159], v[218:221], v[92:95]
	v_mfma_f32_16x16x32_bf16 v[84:87], v[148:151], v[226:229], v[84:87]
	v_mfma_f32_16x16x32_bf16 v[76:79], v[156:159], v[226:229], v[76:79]
	v_mfma_f32_16x16x32_bf16 v[124:127], v[152:155], v[202:205], v[124:127]
	v_mfma_f32_16x16x32_bf16 v[120:123], v[160:163], v[202:205], v[120:123]
	v_mfma_f32_16x16x32_bf16 v[112:115], v[152:155], v[214:217], v[112:115]
	v_mfma_f32_16x16x32_bf16 v[104:107], v[160:163], v[214:217], v[104:107]
	v_mfma_f32_16x16x32_bf16 v[100:103], v[152:155], v[222:225], v[100:103]
	v_mfma_f32_16x16x32_bf16 v[92:95], v[160:163], v[222:225], v[92:95]
	v_mfma_f32_16x16x32_bf16 v[84:87], v[152:155], v[230:233], v[84:87]
	v_mfma_f32_16x16x32_bf16 v[76:79], v[160:163], v[230:233], v[76:79]
	v_mfma_f32_16x16x32_bf16 v[116:119], v[178:181], v[194:197], v[116:119]
	v_mfma_f32_16x16x32_bf16 v[108:111], v[186:189], v[194:197], v[108:111]
	v_mfma_f32_16x16x32_bf16 v[96:99], v[178:181], v[210:213], v[96:99]
	v_mfma_f32_16x16x32_bf16 v[88:91], v[186:189], v[210:213], v[88:91]
	v_mfma_f32_16x16x32_bf16 v[80:83], v[178:181], v[218:221], v[80:83]
	v_mfma_f32_16x16x32_bf16 v[72:75], v[186:189], v[218:221], v[72:75]
	v_mfma_f32_16x16x32_bf16 v[68:71], v[178:181], v[226:229], v[68:71]
	v_mfma_f32_16x16x32_bf16 v[64:67], v[186:189], v[226:229], v[64:67]
	v_mfma_f32_16x16x32_bf16 v[116:119], v[182:185], v[202:205], v[116:119]
	v_mfma_f32_16x16x32_bf16 v[108:111], v[190:193], v[202:205], v[108:111]
	v_mfma_f32_16x16x32_bf16 v[96:99], v[182:185], v[214:217], v[96:99]
	v_mfma_f32_16x16x32_bf16 v[88:91], v[190:193], v[214:217], v[88:91]
	v_mfma_f32_16x16x32_bf16 v[80:83], v[182:185], v[222:225], v[80:83]
	v_mfma_f32_16x16x32_bf16 v[72:75], v[190:193], v[222:225], v[72:75]
	v_mfma_f32_16x16x32_bf16 v[68:71], v[182:185], v[230:233], v[68:71]
	v_mfma_f32_16x16x32_bf16 v[64:67], v[190:193], v[230:233], v[64:67]
	s_setprio 0
	s_barrier
	s_add_i32 s7, s7, s13
	v_lshl_add_u64 v[198:199], v[198:199], 0, s[66:67]
	s_mov_b32 m0, s7
	ds_read_b128 v[194:197], v174 offset:49152
	ds_read_b128 v[202:205], v174 offset:50176
	ds_read_b128 v[210:213], v174 offset:51200
	ds_read_b128 v[214:217], v174 offset:52224
	ds_read_b128 v[218:221], v174 offset:53248
	ds_read_b128 v[222:225], v174 offset:54272
	ds_read_b128 v[226:229], v174 offset:55296
	ds_read_b128 v[230:233], v174 offset:56320
	global_load_lds_dwordx4 v[198:199], off
	s_add_i32 m0, s7, 0x2000
	s_add_u32 s24, s82, 0x40080
	v_lshl_add_u64 v[198:199], v[206:207], 0, s[66:67]
	s_addc_u32 s25, s83, 0
	s_add_i32 s7, s86, s13
	global_load_lds_dwordx4 v[198:199], off
	v_lshl_add_u64 v[198:199], s[24:25], 0, v[132:133]
	s_mov_b32 m0, s7
	s_nop 0
	global_load_lds_dwordx4 v[198:199], off
	v_lshl_add_u64 v[198:199], s[24:25], 0, v[136:137]
	s_add_i32 m0, s7, 0x2000
	s_nop 0
	global_load_lds_dwordx4 v[198:199], off
	v_lshl_add_u64 v[198:199], v[234:235], 0, s[66:67]
	s_mov_b32 m0, s90
	s_nop 0
	global_load_lds_dwordx4 v[198:199], off
	v_lshl_add_u64 v[198:199], v[236:237], 0, s[66:67]
	s_mov_b32 m0, s91
	s_nop 0
	global_load_lds_dwordx4 v[198:199], off
	s_waitcnt vmcnt(6)
	s_waitcnt lgkmcnt(0)
	s_barrier
	s_setprio 1
	v_mfma_f32_16x16x32_bf16 v[60:63], v[148:151], v[194:197], v[60:63]
	v_mfma_f32_16x16x32_bf16 v[56:59], v[156:159], v[194:197], v[56:59]
	v_mfma_f32_16x16x32_bf16 v[52:55], v[148:151], v[210:213], v[52:55]
	v_mfma_f32_16x16x32_bf16 v[44:47], v[156:159], v[210:213], v[44:47]
	v_mfma_f32_16x16x32_bf16 v[36:39], v[148:151], v[218:221], v[36:39]
	v_mfma_f32_16x16x32_bf16 v[28:31], v[156:159], v[218:221], v[28:31]
	v_mfma_f32_16x16x32_bf16 v[20:23], v[148:151], v[226:229], v[20:23]
	v_mfma_f32_16x16x32_bf16 v[12:15], v[156:159], v[226:229], v[12:15]
	v_mfma_f32_16x16x32_bf16 v[60:63], v[152:155], v[202:205], v[60:63]
	v_mfma_f32_16x16x32_bf16 v[56:59], v[160:163], v[202:205], v[56:59]
	v_mfma_f32_16x16x32_bf16 v[52:55], v[152:155], v[214:217], v[52:55]
	v_mfma_f32_16x16x32_bf16 v[44:47], v[160:163], v[214:217], v[44:47]
	v_mfma_f32_16x16x32_bf16 v[36:39], v[152:155], v[222:225], v[36:39]
	v_mfma_f32_16x16x32_bf16 v[28:31], v[160:163], v[222:225], v[28:31]
	v_mfma_f32_16x16x32_bf16 v[20:23], v[152:155], v[230:233], v[20:23]
	v_mfma_f32_16x16x32_bf16 v[12:15], v[160:163], v[230:233], v[12:15]
	v_mfma_f32_16x16x32_bf16 v[48:51], v[178:181], v[194:197], v[48:51]
	v_mfma_f32_16x16x32_bf16 v[40:43], v[186:189], v[194:197], v[40:43]
	v_mfma_f32_16x16x32_bf16 v[32:35], v[178:181], v[210:213], v[32:35]
	v_mfma_f32_16x16x32_bf16 v[24:27], v[186:189], v[210:213], v[24:27]
	v_mfma_f32_16x16x32_bf16 v[16:19], v[178:181], v[218:221], v[16:19]
	v_mfma_f32_16x16x32_bf16 v[8:11], v[186:189], v[218:221], v[8:11]
	v_mfma_f32_16x16x32_bf16 v[4:7], v[178:181], v[226:229], v[4:7]
	v_mfma_f32_16x16x32_bf16 v[0:3], v[186:189], v[226:229], v[0:3]
	v_mfma_f32_16x16x32_bf16 v[48:51], v[182:185], v[202:205], v[48:51]
	v_mfma_f32_16x16x32_bf16 v[40:43], v[190:193], v[202:205], v[40:43]
	v_mfma_f32_16x16x32_bf16 v[32:35], v[182:185], v[214:217], v[32:35]
	v_mfma_f32_16x16x32_bf16 v[24:27], v[190:193], v[214:217], v[24:27]
	v_mfma_f32_16x16x32_bf16 v[16:19], v[182:185], v[222:225], v[16:19]
	v_mfma_f32_16x16x32_bf16 v[8:11], v[190:193], v[222:225], v[8:11]
	v_mfma_f32_16x16x32_bf16 v[4:7], v[182:185], v[230:233], v[4:7]
	v_mfma_f32_16x16x32_bf16 v[0:3], v[190:193], v[230:233], v[0:3]
	s_setprio 0
	s_barrier
	s_add_i32 s6, s6, 2
	s_add_u32 s80, s80, 0x100
	s_addc_u32 s81, s81, 0
	s_add_u32 vcc_hi, vcc_hi, 0x100
	s_addc_u32 s33, s33, 0
	s_cmp_gt_u32 s6, 13
	s_cbranch_scc0 .LBB0_173
	s_and_b64 vcc, exec, s[70:71]
	s_cbranch_vccnz .LBB0_178
	v_lshl_add_u32 v148, s0, 8, v168
	s_cmp_gt_i32 s68, 3
	s_mov_b64 s[0:1], -1
	s_cbranch_scc1 .LBB0_179

.LBB0_241:
	ds_read_b128 v[154:157], v151
	ds_read_b128 v[158:161], v151 offset:1024
	ds_read_b128 v[168:171], v151 offset:2048
	ds_read_b128 v[172:175], v151 offset:3072
	ds_read_b128 v[178:181], v152
	ds_read_b128 v[182:185], v152 offset:1024
	ds_read_b128 v[186:189], v152 offset:2048
	ds_read_b128 v[190:193], v152 offset:3072
	s_add_u32 s24, s76, 0xfffc0080
	s_addc_u32 s25, s77, -1
	s_cmp_eq_u32 s86, 12
	s_cselect_b32 s81, s69, s25
	s_cselect_b32 s80, s75, s24
	s_cselect_b32 s79, s67, s33
	s_cselect_b32 s78, vcc_lo, vcc_hi
	v_lshl_add_u64 v[162:163], s[76:77], 0, v[140:141]
	s_add_i32 m0, s84, 0xc000
	ds_read_b128 v[194:197], v153
	ds_read_b128 v[202:205], v153 offset:1024
	ds_read_b128 v[210:213], v153 offset:2048
	ds_read_b128 v[214:217], v153 offset:3072
	ds_read_b128 v[218:221], v153 offset:4096
	ds_read_b128 v[222:225], v153 offset:5120
	ds_read_b128 v[226:229], v153 offset:6144
	ds_read_b128 v[230:233], v153 offset:7168
	global_load_lds_dwordx4 v[162:163], off
	v_lshl_add_u64 v[162:163], s[76:77], 0, v[142:143]
	s_add_i32 m0, s84, 0xe000
	s_nop 0
	global_load_lds_dwordx4 v[162:163], off
	s_waitcnt vmcnt(8)
	s_waitcnt lgkmcnt(0)
	s_barrier
	s_setprio 1
	v_mfma_f32_16x16x32_bf16 v[124:127], v[154:157], v[194:197], v[124:127]
	v_mfma_f32_16x16x32_bf16 v[120:123], v[168:171], v[194:197], v[120:123]
	v_mfma_f32_16x16x32_bf16 v[112:115], v[154:157], v[210:213], v[112:115]
	v_mfma_f32_16x16x32_bf16 v[104:107], v[168:171], v[210:213], v[104:107]
	v_mfma_f32_16x16x32_bf16 v[100:103], v[154:157], v[218:221], v[100:103]
	v_mfma_f32_16x16x32_bf16 v[92:95], v[168:171], v[218:221], v[92:95]
	v_mfma_f32_16x16x32_bf16 v[84:87], v[154:157], v[226:229], v[84:87]
	v_mfma_f32_16x16x32_bf16 v[76:79], v[168:171], v[226:229], v[76:79]
	v_mfma_f32_16x16x32_bf16 v[124:127], v[158:161], v[202:205], v[124:127]
	v_mfma_f32_16x16x32_bf16 v[120:123], v[172:175], v[202:205], v[120:123]
	v_mfma_f32_16x16x32_bf16 v[112:115], v[158:161], v[214:217], v[112:115]
	v_mfma_f32_16x16x32_bf16 v[104:107], v[172:175], v[214:217], v[104:107]
	v_mfma_f32_16x16x32_bf16 v[100:103], v[158:161], v[222:225], v[100:103]
	v_mfma_f32_16x16x32_bf16 v[92:95], v[172:175], v[222:225], v[92:95]
	v_mfma_f32_16x16x32_bf16 v[84:87], v[158:161], v[230:233], v[84:87]
	v_mfma_f32_16x16x32_bf16 v[76:79], v[172:175], v[230:233], v[76:79]
	v_mfma_f32_16x16x32_bf16 v[116:119], v[178:181], v[194:197], v[116:119]
	v_mfma_f32_16x16x32_bf16 v[108:111], v[186:189], v[194:197], v[108:111]
	v_mfma_f32_16x16x32_bf16 v[96:99], v[178:181], v[210:213], v[96:99]
	v_mfma_f32_16x16x32_bf16 v[88:91], v[186:189], v[210:213], v[88:91]
	v_mfma_f32_16x16x32_bf16 v[80:83], v[178:181], v[218:221], v[80:83]
	v_mfma_f32_16x16x32_bf16 v[72:75], v[186:189], v[218:221], v[72:75]
	v_mfma_f32_16x16x32_bf16 v[68:71], v[178:181], v[226:229], v[68:71]
	v_mfma_f32_16x16x32_bf16 v[64:67], v[186:189], v[226:229], v[64:67]
	v_mfma_f32_16x16x32_bf16 v[116:119], v[182:185], v[202:205], v[116:119]
	v_mfma_f32_16x16x32_bf16 v[108:111], v[190:193], v[202:205], v[108:111]
	v_mfma_f32_16x16x32_bf16 v[96:99], v[182:185], v[214:217], v[96:99]
	v_mfma_f32_16x16x32_bf16 v[88:91], v[190:193], v[214:217], v[88:91]
	v_mfma_f32_16x16x32_bf16 v[80:83], v[182:185], v[222:225], v[80:83]
	v_mfma_f32_16x16x32_bf16 v[72:75], v[190:193], v[222:225], v[72:75]
	v_mfma_f32_16x16x32_bf16 v[68:71], v[182:185], v[230:233], v[68:71]
	v_mfma_f32_16x16x32_bf16 v[64:67], v[190:193], v[230:233], v[64:67]
	s_setprio 0
	s_barrier
	s_add_i32 s24, s94, s83
	v_lshl_add_u64 v[162:163], s[78:79], 0, v[132:133]
	s_mov_b32 m0, s24
	ds_read_b128 v[194:197], v153 offset:16384
	ds_read_b128 v[202:205], v153 offset:17408
	ds_read_b128 v[210:213], v153 offset:18432
	ds_read_b128 v[214:217], v153 offset:19456
	ds_read_b128 v[218:221], v153 offset:20480
	ds_read_b128 v[222:225], v153 offset:21504
	ds_read_b128 v[226:229], v153 offset:22528
	ds_read_b128 v[230:233], v153 offset:23552
	global_load_lds_dwordx4 v[162:163], off
	s_add_i32 m0, s24, 0x2000
	s_add_u32 s24, s78, 0x40000
	v_lshl_add_u64 v[198:199], s[78:79], 0, v[136:137]
	s_addc_u32 s25, s79, 0
	s_add_i32 s52, s95, s83
	global_load_lds_dwordx4 v[198:199], off
	v_lshl_add_u64 v[206:207], s[24:25], 0, v[132:133]
	s_mov_b32 m0, s52
	v_lshl_add_u64 v[234:235], s[80:81], 0, v[134:135]
	global_load_lds_dwordx4 v[206:207], off
	v_lshl_add_u64 v[206:207], s[24:25], 0, v[136:137]
	s_add_i32 m0, s52, 0x2000
	s_nop 0
	global_load_lds_dwordx4 v[206:207], off
	s_waitcnt vmcnt(6)
	s_waitcnt lgkmcnt(0)
	s_barrier
	s_setprio 1
	v_mfma_f32_16x16x32_bf16 v[60:63], v[154:157], v[194:197], v[60:63]
	v_mfma_f32_16x16x32_bf16 v[56:59], v[168:171], v[194:197], v[56:59]
	v_mfma_f32_16x16x32_bf16 v[52:55], v[154:157], v[210:213], v[52:55]
	v_mfma_f32_16x16x32_bf16 v[44:47], v[168:171], v[210:213], v[44:47]
	v_mfma_f32_16x16x32_bf16 v[36:39], v[154:157], v[218:221], v[36:39]
	v_mfma_f32_16x16x32_bf16 v[28:31], v[168:171], v[218:221], v[28:31]
	v_mfma_f32_16x16x32_bf16 v[20:23], v[154:157], v[226:229], v[20:23]
	v_mfma_f32_16x16x32_bf16 v[12:15], v[168:171], v[226:229], v[12:15]
	v_mfma_f32_16x16x32_bf16 v[60:63], v[158:161], v[202:205], v[60:63]
	v_mfma_f32_16x16x32_bf16 v[56:59], v[172:175], v[202:205], v[56:59]
	v_mfma_f32_16x16x32_bf16 v[52:55], v[158:161], v[214:217], v[52:55]
	v_mfma_f32_16x16x32_bf16 v[44:47], v[172:175], v[214:217], v[44:47]
	v_mfma_f32_16x16x32_bf16 v[36:39], v[158:161], v[222:225], v[36:39]
	v_mfma_f32_16x16x32_bf16 v[28:31], v[172:175], v[222:225], v[28:31]
	v_mfma_f32_16x16x32_bf16 v[20:23], v[158:161], v[230:233], v[20:23]
	v_mfma_f32_16x16x32_bf16 v[12:15], v[172:175], v[230:233], v[12:15]
	v_mfma_f32_16x16x32_bf16 v[48:51], v[178:181], v[194:197], v[48:51]
	v_mfma_f32_16x16x32_bf16 v[40:43], v[186:189], v[194:197], v[40:43]
	v_mfma_f32_16x16x32_bf16 v[32:35], v[178:181], v[210:213], v[32:35]
	v_mfma_f32_16x16x32_bf16 v[24:27], v[186:189], v[210:213], v[24:27]
	v_mfma_f32_16x16x32_bf16 v[16:19], v[178:181], v[218:221], v[16:19]
	v_mfma_f32_16x16x32_bf16 v[8:11], v[186:189], v[218:221], v[8:11]
	v_mfma_f32_16x16x32_bf16 v[4:7], v[178:181], v[226:229], v[4:7]
	v_mfma_f32_16x16x32_bf16 v[0:3], v[186:189], v[226:229], v[0:3]
	v_mfma_f32_16x16x32_bf16 v[48:51], v[182:185], v[202:205], v[48:51]
	v_mfma_f32_16x16x32_bf16 v[40:43], v[190:193], v[202:205], v[40:43]
	v_mfma_f32_16x16x32_bf16 v[32:35], v[182:185], v[214:217], v[32:35]
	v_mfma_f32_16x16x32_bf16 v[24:27], v[190:193], v[214:217], v[24:27]
	v_mfma_f32_16x16x32_bf16 v[16:19], v[182:185], v[222:225], v[16:19]
	v_mfma_f32_16x16x32_bf16 v[8:11], v[190:193], v[222:225], v[8:11]
	v_mfma_f32_16x16x32_bf16 v[4:7], v[182:185], v[230:233], v[4:7]
	v_mfma_f32_16x16x32_bf16 v[0:3], v[190:193], v[230:233], v[0:3]
	s_setprio 0
	s_barrier
	s_add_i32 s52, 0, 0x18000
	v_add_u32_e32 v138, s52, v149
	s_add_i32 s53, 0, 0x1c000
	ds_read_b128 v[154:157], v138
	ds_read_b128 v[158:161], v138 offset:1024
	ds_read_b128 v[168:171], v138 offset:2048
	ds_read_b128 v[172:175], v138 offset:3072
	v_add_u32_e32 v138, s53, v149
	ds_read_b128 v[178:181], v138
	ds_read_b128 v[182:185], v138 offset:1024
	ds_read_b128 v[186:189], v138 offset:2048
	ds_read_b128 v[190:193], v138 offset:3072
	v_lshl_add_u64 v[206:207], s[80:81], 0, v[130:131]
	s_mov_b32 m0, s84
	s_nop 0
	global_load_lds_dwordx4 v[206:207], off
	s_mov_b32 m0, s85
	s_nop 0
	global_load_lds_dwordx4 v[234:235], off
	s_add_u32 s24, s80, 0x40000
	s_addc_u32 s25, s81, 0
	s_mov_b32 m0, s87
	v_lshl_add_u64 v[236:237], s[24:25], 0, v[130:131]
	ds_read_b128 v[194:197], v153 offset:32768
	ds_read_b128 v[202:205], v153 offset:33792
	ds_read_b128 v[210:213], v153 offset:34816
	ds_read_b128 v[214:217], v153 offset:35840
	ds_read_b128 v[218:221], v153 offset:36864
	ds_read_b128 v[222:225], v153 offset:37888
	ds_read_b128 v[226:229], v153 offset:38912
	ds_read_b128 v[230:233], v153 offset:39936
	global_load_lds_dwordx4 v[236:237], off
	v_lshl_add_u64 v[236:237], s[24:25], 0, v[134:135]
	s_mov_b32 m0, s88
	s_nop 0
	global_load_lds_dwordx4 v[236:237], off
	s_waitcnt vmcnt(8)
	s_waitcnt lgkmcnt(0)
	s_barrier
	s_setprio 1
	v_mfma_f32_16x16x32_bf16 v[124:127], v[154:157], v[194:197], v[124:127]
	v_mfma_f32_16x16x32_bf16 v[120:123], v[168:171], v[194:197], v[120:123]
	v_mfma_f32_16x16x32_bf16 v[112:115], v[154:157], v[210:213], v[112:115]
	v_mfma_f32_16x16x32_bf16 v[104:107], v[168:171], v[210:213], v[104:107]
	v_mfma_f32_16x16x32_bf16 v[100:103], v[154:157], v[218:221], v[100:103]
	v_mfma_f32_16x16x32_bf16 v[92:95], v[168:171], v[218:221], v[92:95]
	v_mfma_f32_16x16x32_bf16 v[84:87], v[154:157], v[226:229], v[84:87]
	v_mfma_f32_16x16x32_bf16 v[76:79], v[168:171], v[226:229], v[76:79]
	v_mfma_f32_16x16x32_bf16 v[124:127], v[158:161], v[202:205], v[124:127]
	v_mfma_f32_16x16x32_bf16 v[120:123], v[172:175], v[202:205], v[120:123]
	v_mfma_f32_16x16x32_bf16 v[112:115], v[158:161], v[214:217], v[112:115]
	v_mfma_f32_16x16x32_bf16 v[104:107], v[172:175], v[214:217], v[104:107]
	v_mfma_f32_16x16x32_bf16 v[100:103], v[158:161], v[222:225], v[100:103]
	v_mfma_f32_16x16x32_bf16 v[92:95], v[172:175], v[222:225], v[92:95]
	v_mfma_f32_16x16x32_bf16 v[84:87], v[158:161], v[230:233], v[84:87]
	v_mfma_f32_16x16x32_bf16 v[76:79], v[172:175], v[230:233], v[76:79]
	v_mfma_f32_16x16x32_bf16 v[116:119], v[178:181], v[194:197], v[116:119]
	v_mfma_f32_16x16x32_bf16 v[108:111], v[186:189], v[194:197], v[108:111]
	v_mfma_f32_16x16x32_bf16 v[96:99], v[178:181], v[210:213], v[96:99]
	v_mfma_f32_16x16x32_bf16 v[88:91], v[186:189], v[210:213], v[88:91]
	v_mfma_f32_16x16x32_bf16 v[80:83], v[178:181], v[218:221], v[80:83]
	v_mfma_f32_16x16x32_bf16 v[72:75], v[186:189], v[218:221], v[72:75]
	v_mfma_f32_16x16x32_bf16 v[68:71], v[178:181], v[226:229], v[68:71]
	v_mfma_f32_16x16x32_bf16 v[64:67], v[186:189], v[226:229], v[64:67]
	v_mfma_f32_16x16x32_bf16 v[116:119], v[182:185], v[202:205], v[116:119]
	v_mfma_f32_16x16x32_bf16 v[108:111], v[190:193], v[202:205], v[108:111]
	v_mfma_f32_16x16x32_bf16 v[96:99], v[182:185], v[214:217], v[96:99]
	v_mfma_f32_16x16x32_bf16 v[88:91], v[190:193], v[214:217], v[88:91]
	v_mfma_f32_16x16x32_bf16 v[80:83], v[182:185], v[222:225], v[80:83]
	v_mfma_f32_16x16x32_bf16 v[72:75], v[190:193], v[222:225], v[72:75]
	v_mfma_f32_16x16x32_bf16 v[68:71], v[182:185], v[230:233], v[68:71]
	v_mfma_f32_16x16x32_bf16 v[64:67], v[190:193], v[230:233], v[64:67]
	s_setprio 0
	s_barrier
	s_add_i32 s24, s52, s83
	v_lshl_add_u64 v[162:163], v[162:163], 0, s[26:27]
	s_mov_b32 m0, s24
	ds_read_b128 v[194:197], v153 offset:49152
	ds_read_b128 v[202:205], v153 offset:50176
	ds_read_b128 v[210:213], v153 offset:51200
	ds_read_b128 v[214:217], v153 offset:52224
	ds_read_b128 v[218:221], v153 offset:53248
	ds_read_b128 v[222:225], v153 offset:54272
	ds_read_b128 v[226:229], v153 offset:55296
	ds_read_b128 v[230:233], v153 offset:56320
	global_load_lds_dwordx4 v[162:163], off
	s_add_i32 m0, s24, 0x2000
	s_add_u32 s24, s78, 0x40080
	v_lshl_add_u64 v[162:163], v[198:199], 0, s[26:27]
	s_addc_u32 s25, s79, 0
	s_add_i32 s52, s53, s83
	global_load_lds_dwordx4 v[162:163], off
	v_lshl_add_u64 v[162:163], s[24:25], 0, v[132:133]
	s_mov_b32 m0, s52
	s_nop 0
	global_load_lds_dwordx4 v[162:163], off
	v_lshl_add_u64 v[162:163], s[24:25], 0, v[136:137]
	s_add_i32 m0, s52, 0x2000
	s_nop 0
	global_load_lds_dwordx4 v[162:163], off
	v_lshl_add_u64 v[162:163], v[206:207], 0, s[26:27]
	s_mov_b32 m0, s90
	s_nop 0
	global_load_lds_dwordx4 v[162:163], off
	v_lshl_add_u64 v[162:163], v[234:235], 0, s[26:27]
	s_mov_b32 m0, s91
	s_nop 0
	global_load_lds_dwordx4 v[162:163], off
	s_waitcnt vmcnt(6)
	s_waitcnt lgkmcnt(0)
	s_barrier
	s_setprio 1
	v_mfma_f32_16x16x32_bf16 v[60:63], v[154:157], v[194:197], v[60:63]
	v_mfma_f32_16x16x32_bf16 v[56:59], v[168:171], v[194:197], v[56:59]
	v_mfma_f32_16x16x32_bf16 v[52:55], v[154:157], v[210:213], v[52:55]
	v_mfma_f32_16x16x32_bf16 v[44:47], v[168:171], v[210:213], v[44:47]
	v_mfma_f32_16x16x32_bf16 v[36:39], v[154:157], v[218:221], v[36:39]
	v_mfma_f32_16x16x32_bf16 v[28:31], v[168:171], v[218:221], v[28:31]
	v_mfma_f32_16x16x32_bf16 v[20:23], v[154:157], v[226:229], v[20:23]
	v_mfma_f32_16x16x32_bf16 v[12:15], v[168:171], v[226:229], v[12:15]
	v_mfma_f32_16x16x32_bf16 v[60:63], v[158:161], v[202:205], v[60:63]
	v_mfma_f32_16x16x32_bf16 v[56:59], v[172:175], v[202:205], v[56:59]
	v_mfma_f32_16x16x32_bf16 v[52:55], v[158:161], v[214:217], v[52:55]
	v_mfma_f32_16x16x32_bf16 v[44:47], v[172:175], v[214:217], v[44:47]
	v_mfma_f32_16x16x32_bf16 v[36:39], v[158:161], v[222:225], v[36:39]
	v_mfma_f32_16x16x32_bf16 v[28:31], v[172:175], v[222:225], v[28:31]
	v_mfma_f32_16x16x32_bf16 v[20:23], v[158:161], v[230:233], v[20:23]
	v_mfma_f32_16x16x32_bf16 v[12:15], v[172:175], v[230:233], v[12:15]
	v_mfma_f32_16x16x32_bf16 v[48:51], v[178:181], v[194:197], v[48:51]
	v_mfma_f32_16x16x32_bf16 v[40:43], v[186:189], v[194:197], v[40:43]
	v_mfma_f32_16x16x32_bf16 v[32:35], v[178:181], v[210:213], v[32:35]
	v_mfma_f32_16x16x32_bf16 v[24:27], v[186:189], v[210:213], v[24:27]
	v_mfma_f32_16x16x32_bf16 v[16:19], v[178:181], v[218:221], v[16:19]
	v_mfma_f32_16x16x32_bf16 v[8:11], v[186:189], v[218:221], v[8:11]
	v_mfma_f32_16x16x32_bf16 v[4:7], v[178:181], v[226:229], v[4:7]
	v_mfma_f32_16x16x32_bf16 v[0:3], v[186:189], v[226:229], v[0:3]
	v_mfma_f32_16x16x32_bf16 v[48:51], v[182:185], v[202:205], v[48:51]
	v_mfma_f32_16x16x32_bf16 v[40:43], v[190:193], v[202:205], v[40:43]
	v_mfma_f32_16x16x32_bf16 v[32:35], v[182:185], v[214:217], v[32:35]
	v_mfma_f32_16x16x32_bf16 v[24:27], v[190:193], v[214:217], v[24:27]
	v_mfma_f32_16x16x32_bf16 v[16:19], v[182:185], v[222:225], v[16:19]
	v_mfma_f32_16x16x32_bf16 v[8:11], v[190:193], v[222:225], v[8:11]
	v_mfma_f32_16x16x32_bf16 v[4:7], v[182:185], v[230:233], v[4:7]
	v_mfma_f32_16x16x32_bf16 v[0:3], v[190:193], v[230:233], v[0:3]
	s_setprio 0
	s_barrier
	s_add_i32 s86, s86, 2
	s_add_u32 s76, s76, 0x100
	s_addc_u32 s77, s77, 0
	s_add_u32 vcc_hi, vcc_hi, 0x100
	s_addc_u32 s33, s33, 0
	s_cmp_gt_u32 s86, 13
	s_cbranch_scc0 .LBB0_241
	s_and_b64 vcc, exec, s[34:35]
	s_cbranch_vccz .LBB0_244
	s_barrier

.LBB0_462:
	v_add_u32_e32 v156, s83, v161
	v_add_u32_e32 v176, s84, v161
	ds_read_b128 v[144:147], v156
	ds_read_b128 v[148:151], v156 offset:1024
	ds_read_b128 v[152:155], v156 offset:2048
	ds_read_b128 v[156:159], v156 offset:3072
	ds_read_b128 v[164:167], v176
	ds_read_b128 v[168:171], v176 offset:1024
	ds_read_b128 v[172:175], v176 offset:2048
	ds_read_b128 v[176:179], v176 offset:3072
	s_add_u32 s58, s70, 0xfffe0080
	s_addc_u32 s59, s71, -1
	s_cmp_eq_u32 s95, 4
	s_cselect_b32 s75, s57, s59
	s_cselect_b32 s74, s91, s58
	s_cselect_b32 s73, s55, s94
	s_cselect_b32 s72, s92, s93
	v_lshl_add_u64 v[216:217], s[70:71], 0, v[136:137]
	s_add_i32 m0, s77, 0xc000
	ds_read_b128 v[180:183], v163
	ds_read_b128 v[184:187], v163 offset:1024
	ds_read_b128 v[188:191], v163 offset:2048
	ds_read_b128 v[192:195], v163 offset:3072
	ds_read_b128 v[196:199], v163 offset:4096
	ds_read_b128 v[200:203], v163 offset:5120
	ds_read_b128 v[204:207], v163 offset:6144
	ds_read_b128 v[212:215], v163 offset:7168
	global_load_lds_dwordx4 v[216:217], off
	v_lshl_add_u64 v[216:217], s[70:71], 0, v[138:139]
	s_add_i32 m0, s77, 0xe000
	s_nop 0
	global_load_lds_dwordx4 v[216:217], off
	s_waitcnt vmcnt(8)
	s_waitcnt lgkmcnt(0)
	s_barrier
	s_setprio 1
	v_mfma_f32_16x16x32_bf16 v[124:127], v[144:147], v[180:183], v[124:127]
	v_mfma_f32_16x16x32_bf16 v[120:123], v[152:155], v[180:183], v[120:123]
	v_mfma_f32_16x16x32_bf16 v[116:119], v[144:147], v[188:191], v[116:119]
	v_mfma_f32_16x16x32_bf16 v[112:115], v[152:155], v[188:191], v[112:115]
	v_mfma_f32_16x16x32_bf16 v[108:111], v[144:147], v[196:199], v[108:111]
	v_mfma_f32_16x16x32_bf16 v[104:107], v[152:155], v[196:199], v[104:107]
	v_mfma_f32_16x16x32_bf16 v[100:103], v[144:147], v[204:207], v[100:103]
	v_mfma_f32_16x16x32_bf16 v[96:99], v[152:155], v[204:207], v[96:99]
	v_mfma_f32_16x16x32_bf16 v[124:127], v[148:151], v[184:187], v[124:127]
	v_mfma_f32_16x16x32_bf16 v[120:123], v[156:159], v[184:187], v[120:123]
	v_mfma_f32_16x16x32_bf16 v[116:119], v[148:151], v[192:195], v[116:119]
	v_mfma_f32_16x16x32_bf16 v[112:115], v[156:159], v[192:195], v[112:115]
	v_mfma_f32_16x16x32_bf16 v[108:111], v[148:151], v[200:203], v[108:111]
	v_mfma_f32_16x16x32_bf16 v[104:107], v[156:159], v[200:203], v[104:107]
	v_mfma_f32_16x16x32_bf16 v[100:103], v[148:151], v[212:215], v[100:103]
	v_mfma_f32_16x16x32_bf16 v[96:99], v[156:159], v[212:215], v[96:99]
	v_mfma_f32_16x16x32_bf16 v[92:95], v[164:167], v[180:183], v[92:95]
	v_mfma_f32_16x16x32_bf16 v[88:91], v[172:175], v[180:183], v[88:91]
	v_mfma_f32_16x16x32_bf16 v[84:87], v[164:167], v[188:191], v[84:87]
	v_mfma_f32_16x16x32_bf16 v[80:83], v[172:175], v[188:191], v[80:83]
	v_mfma_f32_16x16x32_bf16 v[76:79], v[164:167], v[196:199], v[76:79]
	v_mfma_f32_16x16x32_bf16 v[72:75], v[172:175], v[196:199], v[72:75]
	v_mfma_f32_16x16x32_bf16 v[68:71], v[164:167], v[204:207], v[68:71]
	v_mfma_f32_16x16x32_bf16 v[64:67], v[172:175], v[204:207], v[64:67]
	v_mfma_f32_16x16x32_bf16 v[92:95], v[168:171], v[184:187], v[92:95]
	v_mfma_f32_16x16x32_bf16 v[88:91], v[176:179], v[184:187], v[88:91]
	v_mfma_f32_16x16x32_bf16 v[84:87], v[168:171], v[192:195], v[84:87]
	v_mfma_f32_16x16x32_bf16 v[80:83], v[176:179], v[192:195], v[80:83]
	v_mfma_f32_16x16x32_bf16 v[76:79], v[168:171], v[200:203], v[76:79]
	v_mfma_f32_16x16x32_bf16 v[72:75], v[176:179], v[200:203], v[72:75]
	v_mfma_f32_16x16x32_bf16 v[68:71], v[168:171], v[212:215], v[68:71]
	v_mfma_f32_16x16x32_bf16 v[64:67], v[176:179], v[212:215], v[64:67]
	s_setprio 0
	s_barrier
	s_add_i32 s58, s83, s76
	v_lshl_add_u64 v[216:217], s[72:73], 0, v[130:131]
	s_mov_b32 m0, s58
	ds_read_b128 v[180:183], v163 offset:16384
	ds_read_b128 v[184:187], v163 offset:17408
	ds_read_b128 v[188:191], v163 offset:18432
	ds_read_b128 v[192:195], v163 offset:19456
	ds_read_b128 v[196:199], v163 offset:20480
	ds_read_b128 v[200:203], v163 offset:21504
	ds_read_b128 v[204:207], v163 offset:22528
	ds_read_b128 v[212:215], v163 offset:23552
	global_load_lds_dwordx4 v[216:217], off
	s_add_i32 m0, s58, 0x2000
	s_add_u32 s96, s72, 0x20000
	v_lshl_add_u64 v[218:219], s[72:73], 0, v[134:135]
	s_addc_u32 s97, s73, 0
	s_add_i32 s58, s84, s76
	global_load_lds_dwordx4 v[218:219], off
	v_lshl_add_u64 v[220:221], s[96:97], 0, v[130:131]
	s_mov_b32 m0, s58
	v_lshl_add_u64 v[222:223], s[74:75], 0, v[132:133]
	global_load_lds_dwordx4 v[220:221], off
	v_lshl_add_u64 v[220:221], s[96:97], 0, v[134:135]
	s_add_i32 m0, s58, 0x2000
	s_nop 0
	global_load_lds_dwordx4 v[220:221], off
	s_waitcnt vmcnt(6)
	s_waitcnt lgkmcnt(0)
	s_barrier
	s_setprio 1
	v_mfma_f32_16x16x32_bf16 v[60:63], v[144:147], v[180:183], v[60:63]
	v_mfma_f32_16x16x32_bf16 v[56:59], v[152:155], v[180:183], v[56:59]
	v_mfma_f32_16x16x32_bf16 v[52:55], v[144:147], v[188:191], v[52:55]
	v_mfma_f32_16x16x32_bf16 v[48:51], v[152:155], v[188:191], v[48:51]
	v_mfma_f32_16x16x32_bf16 v[44:47], v[144:147], v[196:199], v[44:47]
	v_mfma_f32_16x16x32_bf16 v[40:43], v[152:155], v[196:199], v[40:43]
	v_mfma_f32_16x16x32_bf16 v[36:39], v[144:147], v[204:207], v[36:39]
	v_mfma_f32_16x16x32_bf16 v[32:35], v[152:155], v[204:207], v[32:35]
	v_mfma_f32_16x16x32_bf16 v[60:63], v[148:151], v[184:187], v[60:63]
	v_mfma_f32_16x16x32_bf16 v[56:59], v[156:159], v[184:187], v[56:59]
	v_mfma_f32_16x16x32_bf16 v[52:55], v[148:151], v[192:195], v[52:55]
	v_mfma_f32_16x16x32_bf16 v[48:51], v[156:159], v[192:195], v[48:51]
	v_mfma_f32_16x16x32_bf16 v[44:47], v[148:151], v[200:203], v[44:47]
	v_mfma_f32_16x16x32_bf16 v[40:43], v[156:159], v[200:203], v[40:43]
	v_mfma_f32_16x16x32_bf16 v[36:39], v[148:151], v[212:215], v[36:39]
	v_mfma_f32_16x16x32_bf16 v[32:35], v[156:159], v[212:215], v[32:35]
	v_mfma_f32_16x16x32_bf16 v[28:31], v[164:167], v[180:183], v[28:31]
	v_mfma_f32_16x16x32_bf16 v[24:27], v[172:175], v[180:183], v[24:27]
	v_mfma_f32_16x16x32_bf16 v[20:23], v[164:167], v[188:191], v[20:23]
	v_mfma_f32_16x16x32_bf16 v[16:19], v[172:175], v[188:191], v[16:19]
	v_mfma_f32_16x16x32_bf16 v[12:15], v[164:167], v[196:199], v[12:15]
	v_mfma_f32_16x16x32_bf16 v[8:11], v[172:175], v[196:199], v[8:11]
	v_mfma_f32_16x16x32_bf16 v[4:7], v[164:167], v[204:207], v[4:7]
	v_mfma_f32_16x16x32_bf16 v[0:3], v[172:175], v[204:207], v[0:3]
	v_mfma_f32_16x16x32_bf16 v[28:31], v[168:171], v[184:187], v[28:31]
	v_mfma_f32_16x16x32_bf16 v[24:27], v[176:179], v[184:187], v[24:27]
	v_mfma_f32_16x16x32_bf16 v[20:23], v[168:171], v[192:195], v[20:23]
	v_mfma_f32_16x16x32_bf16 v[16:19], v[176:179], v[192:195], v[16:19]
	v_mfma_f32_16x16x32_bf16 v[12:15], v[168:171], v[200:203], v[12:15]
	v_mfma_f32_16x16x32_bf16 v[8:11], v[176:179], v[200:203], v[8:11]
	v_mfma_f32_16x16x32_bf16 v[4:7], v[168:171], v[212:215], v[4:7]
	v_mfma_f32_16x16x32_bf16 v[0:3], v[176:179], v[212:215], v[0:3]
	s_setprio 0
	s_barrier
	s_add_i32 s58, 0, 0x18000
	s_add_i32 s59, 0, 0x1c000
	v_add_u32_e32 v156, s58, v161
	v_add_u32_e32 v176, s59, v161
	ds_read_b128 v[144:147], v156
	ds_read_b128 v[148:151], v156 offset:1024
	ds_read_b128 v[152:155], v156 offset:2048
	ds_read_b128 v[156:159], v156 offset:3072
	ds_read_b128 v[164:167], v176
	ds_read_b128 v[168:171], v176 offset:1024
	ds_read_b128 v[172:175], v176 offset:2048
	ds_read_b128 v[176:179], v176 offset:3072
	v_lshl_add_u64 v[220:221], s[74:75], 0, v[128:129]
	s_mov_b32 m0, s77
	s_nop 0
	global_load_lds_dwordx4 v[220:221], off
	s_mov_b32 m0, s78
	s_nop 0
	global_load_lds_dwordx4 v[222:223], off
	s_add_u32 s74, s74, 0x20000
	s_addc_u32 s75, s75, 0
	s_mov_b32 m0, s79
	v_lshl_add_u64 v[224:225], s[74:75], 0, v[128:129]
	ds_read_b128 v[180:183], v163 offset:32768
	ds_read_b128 v[184:187], v163 offset:33792
	ds_read_b128 v[188:191], v163 offset:34816
	ds_read_b128 v[192:195], v163 offset:35840
	ds_read_b128 v[196:199], v163 offset:36864
	ds_read_b128 v[200:203], v163 offset:37888
	ds_read_b128 v[204:207], v163 offset:38912
	ds_read_b128 v[212:215], v163 offset:39936
	global_load_lds_dwordx4 v[224:225], off
	v_lshl_add_u64 v[224:225], s[74:75], 0, v[132:133]
	s_mov_b32 m0, s80
	s_nop 0
	global_load_lds_dwordx4 v[224:225], off
	s_waitcnt vmcnt(8)
	s_waitcnt lgkmcnt(0)
	s_barrier
	s_setprio 1
	v_mfma_f32_16x16x32_bf16 v[124:127], v[144:147], v[180:183], v[124:127]
	v_mfma_f32_16x16x32_bf16 v[120:123], v[152:155], v[180:183], v[120:123]
	v_mfma_f32_16x16x32_bf16 v[116:119], v[144:147], v[188:191], v[116:119]
	v_mfma_f32_16x16x32_bf16 v[112:115], v[152:155], v[188:191], v[112:115]
	v_mfma_f32_16x16x32_bf16 v[108:111], v[144:147], v[196:199], v[108:111]
	v_mfma_f32_16x16x32_bf16 v[104:107], v[152:155], v[196:199], v[104:107]
	v_mfma_f32_16x16x32_bf16 v[100:103], v[144:147], v[204:207], v[100:103]
	v_mfma_f32_16x16x32_bf16 v[96:99], v[152:155], v[204:207], v[96:99]
	v_mfma_f32_16x16x32_bf16 v[124:127], v[148:151], v[184:187], v[124:127]
	v_mfma_f32_16x16x32_bf16 v[120:123], v[156:159], v[184:187], v[120:123]
	v_mfma_f32_16x16x32_bf16 v[116:119], v[148:151], v[192:195], v[116:119]
	v_mfma_f32_16x16x32_bf16 v[112:115], v[156:159], v[192:195], v[112:115]
	v_mfma_f32_16x16x32_bf16 v[108:111], v[148:151], v[200:203], v[108:111]
	v_mfma_f32_16x16x32_bf16 v[104:107], v[156:159], v[200:203], v[104:107]
	v_mfma_f32_16x16x32_bf16 v[100:103], v[148:151], v[212:215], v[100:103]
	v_mfma_f32_16x16x32_bf16 v[96:99], v[156:159], v[212:215], v[96:99]
	v_mfma_f32_16x16x32_bf16 v[92:95], v[164:167], v[180:183], v[92:95]
	v_mfma_f32_16x16x32_bf16 v[88:91], v[172:175], v[180:183], v[88:91]
	v_mfma_f32_16x16x32_bf16 v[84:87], v[164:167], v[188:191], v[84:87]
	v_mfma_f32_16x16x32_bf16 v[80:83], v[172:175], v[188:191], v[80:83]
	v_mfma_f32_16x16x32_bf16 v[76:79], v[164:167], v[196:199], v[76:79]
	v_mfma_f32_16x16x32_bf16 v[72:75], v[172:175], v[196:199], v[72:75]
	v_mfma_f32_16x16x32_bf16 v[68:71], v[164:167], v[204:207], v[68:71]
	v_mfma_f32_16x16x32_bf16 v[64:67], v[172:175], v[204:207], v[64:67]
	v_mfma_f32_16x16x32_bf16 v[92:95], v[168:171], v[184:187], v[92:95]
	v_mfma_f32_16x16x32_bf16 v[88:91], v[176:179], v[184:187], v[88:91]
	v_mfma_f32_16x16x32_bf16 v[84:87], v[168:171], v[192:195], v[84:87]
	v_mfma_f32_16x16x32_bf16 v[80:83], v[176:179], v[192:195], v[80:83]
	v_mfma_f32_16x16x32_bf16 v[76:79], v[168:171], v[200:203], v[76:79]
	v_mfma_f32_16x16x32_bf16 v[72:75], v[176:179], v[200:203], v[72:75]
	v_mfma_f32_16x16x32_bf16 v[68:71], v[168:171], v[212:215], v[68:71]
	v_mfma_f32_16x16x32_bf16 v[64:67], v[176:179], v[212:215], v[64:67]
	s_setprio 0
	s_barrier
	s_add_i32 s58, s58, s76
	v_lshl_add_u64 v[216:217], v[216:217], 0, s[38:39]
	s_mov_b32 m0, s58
	ds_read_b128 v[180:183], v163 offset:49152
	ds_read_b128 v[184:187], v163 offset:50176
	ds_read_b128 v[188:191], v163 offset:51200
	ds_read_b128 v[192:195], v163 offset:52224
	ds_read_b128 v[196:199], v163 offset:53248
	ds_read_b128 v[200:203], v163 offset:54272
	ds_read_b128 v[204:207], v163 offset:55296
	ds_read_b128 v[212:215], v163 offset:56320
	global_load_lds_dwordx4 v[216:217], off
	s_add_i32 m0, s58, 0x2000
	s_add_u32 s72, s72, 0x20080
	v_lshl_add_u64 v[216:217], v[218:219], 0, s[38:39]
	s_addc_u32 s73, s73, 0
	s_add_i32 s58, s59, s76
	global_load_lds_dwordx4 v[216:217], off
	v_lshl_add_u64 v[216:217], s[72:73], 0, v[130:131]
	s_mov_b32 m0, s58
	s_nop 0
	global_load_lds_dwordx4 v[216:217], off
	v_lshl_add_u64 v[216:217], s[72:73], 0, v[134:135]
	s_add_i32 m0, s58, 0x2000
	s_nop 0
	global_load_lds_dwordx4 v[216:217], off
	v_lshl_add_u64 v[216:217], v[220:221], 0, s[38:39]
	s_mov_b32 m0, s81
	s_nop 0
	global_load_lds_dwordx4 v[216:217], off
	v_lshl_add_u64 v[216:217], v[222:223], 0, s[38:39]
	s_mov_b32 m0, s82
	s_nop 0
	global_load_lds_dwordx4 v[216:217], off
	s_waitcnt vmcnt(6)
	s_waitcnt lgkmcnt(0)
	s_barrier
	s_setprio 1
	v_mfma_f32_16x16x32_bf16 v[60:63], v[144:147], v[180:183], v[60:63]
	v_mfma_f32_16x16x32_bf16 v[56:59], v[152:155], v[180:183], v[56:59]
	v_mfma_f32_16x16x32_bf16 v[52:55], v[144:147], v[188:191], v[52:55]
	v_mfma_f32_16x16x32_bf16 v[48:51], v[152:155], v[188:191], v[48:51]
	v_mfma_f32_16x16x32_bf16 v[44:47], v[144:147], v[196:199], v[44:47]
	v_mfma_f32_16x16x32_bf16 v[40:43], v[152:155], v[196:199], v[40:43]
	v_mfma_f32_16x16x32_bf16 v[36:39], v[144:147], v[204:207], v[36:39]
	v_mfma_f32_16x16x32_bf16 v[32:35], v[152:155], v[204:207], v[32:35]
	v_mfma_f32_16x16x32_bf16 v[60:63], v[148:151], v[184:187], v[60:63]
	v_mfma_f32_16x16x32_bf16 v[56:59], v[156:159], v[184:187], v[56:59]
	v_mfma_f32_16x16x32_bf16 v[52:55], v[148:151], v[192:195], v[52:55]
	v_mfma_f32_16x16x32_bf16 v[48:51], v[156:159], v[192:195], v[48:51]
	v_mfma_f32_16x16x32_bf16 v[44:47], v[148:151], v[200:203], v[44:47]
	v_mfma_f32_16x16x32_bf16 v[40:43], v[156:159], v[200:203], v[40:43]
	v_mfma_f32_16x16x32_bf16 v[36:39], v[148:151], v[212:215], v[36:39]
	v_mfma_f32_16x16x32_bf16 v[32:35], v[156:159], v[212:215], v[32:35]
	v_mfma_f32_16x16x32_bf16 v[28:31], v[164:167], v[180:183], v[28:31]
	v_mfma_f32_16x16x32_bf16 v[24:27], v[172:175], v[180:183], v[24:27]
	v_mfma_f32_16x16x32_bf16 v[20:23], v[164:167], v[188:191], v[20:23]
	v_mfma_f32_16x16x32_bf16 v[16:19], v[172:175], v[188:191], v[16:19]
	v_mfma_f32_16x16x32_bf16 v[12:15], v[164:167], v[196:199], v[12:15]
	v_mfma_f32_16x16x32_bf16 v[8:11], v[172:175], v[196:199], v[8:11]
	v_mfma_f32_16x16x32_bf16 v[4:7], v[164:167], v[204:207], v[4:7]
	v_mfma_f32_16x16x32_bf16 v[0:3], v[172:175], v[204:207], v[0:3]
	v_mfma_f32_16x16x32_bf16 v[28:31], v[168:171], v[184:187], v[28:31]
	v_mfma_f32_16x16x32_bf16 v[24:27], v[176:179], v[184:187], v[24:27]
	v_mfma_f32_16x16x32_bf16 v[20:23], v[168:171], v[192:195], v[20:23]
	v_mfma_f32_16x16x32_bf16 v[16:19], v[176:179], v[192:195], v[16:19]
	v_mfma_f32_16x16x32_bf16 v[12:15], v[168:171], v[200:203], v[12:15]
	v_mfma_f32_16x16x32_bf16 v[8:11], v[176:179], v[200:203], v[8:11]
	v_mfma_f32_16x16x32_bf16 v[4:7], v[168:171], v[212:215], v[4:7]
	v_mfma_f32_16x16x32_bf16 v[0:3], v[176:179], v[212:215], v[0:3]
	s_setprio 0
	s_barrier
	s_add_i32 s95, s95, 2
	s_add_u32 s70, s70, 0x100
	s_addc_u32 s71, s71, 0
	s_add_u32 s93, s93, 0x100
	s_addc_u32 s94, s94, 0
	s_cmp_gt_u32 s95, 5
	s_cbranch_scc0 .LBB0_462
	s_and_b64 vcc, exec, s[40:41]
	s_cbranch_vccz .LBB0_465
	s_barrier

.LBB0_544:
	ds_read_b128 v[100:103], v199
	ds_read_b128 v[108:111], v199 offset:1024
	ds_read_b128 v[112:115], v199 offset:2048
	ds_read_b128 v[116:119], v199 offset:3072
	ds_read_b128 v[156:159], v200
	ds_read_b128 v[160:163], v200 offset:1024
	ds_read_b128 v[164:167], v200 offset:2048
	ds_read_b128 v[168:171], v200 offset:3072
	s_add_u32 s56, s54, 0xfffc0080
	s_addc_u32 s57, s55, -1
	s_cmp_eq_u32 s88, 12
	s_cselect_b32 s65, s43, s57
	s_cselect_b32 s64, s49, s56
	s_cselect_b32 s57, s41, s33
	s_cselect_b32 s56, s53, s87
	v_lshl_add_u64 v[216:217], s[54:55], 0, v[148:149]
	s_add_i32 m0, s67, 0xc000
	ds_read_b128 v[172:175], v201
	ds_read_b128 v[176:179], v201 offset:1024
	ds_read_b128 v[180:183], v201 offset:2048
	ds_read_b128 v[184:187], v201 offset:3072
	ds_read_b128 v[188:191], v201 offset:4096
	ds_read_b128 v[192:195], v201 offset:5120
	ds_read_b128 v[204:207], v201 offset:6144
	ds_read_b128 v[212:215], v201 offset:7168
	global_load_lds_dwordx4 v[216:217], off
	v_lshl_add_u64 v[216:217], s[54:55], 0, v[150:151]
	s_add_i32 m0, s67, 0xe000
	s_nop 0
	global_load_lds_dwordx4 v[216:217], off
	s_waitcnt vmcnt(8)
	s_waitcnt lgkmcnt(0)
	s_barrier
	s_setprio 1
	v_mfma_f32_16x16x32_bf16 v[140:143], v[100:103], v[172:175], v[140:143]
	v_mfma_f32_16x16x32_bf16 v[136:139], v[112:115], v[172:175], v[136:139]
	v_mfma_f32_16x16x32_bf16 v[124:127], v[100:103], v[180:183], v[124:127]
	v_mfma_f32_16x16x32_bf16 v[120:123], v[112:115], v[180:183], v[120:123]
	v_mfma_f32_16x16x32_bf16 v[92:95], v[100:103], v[188:191], v[92:95]
	v_mfma_f32_16x16x32_bf16 v[88:91], v[112:115], v[188:191], v[88:91]
	v_mfma_f32_16x16x32_bf16 v[76:79], v[100:103], v[204:207], v[76:79]
	v_mfma_f32_16x16x32_bf16 v[72:75], v[112:115], v[204:207], v[72:75]
	v_mfma_f32_16x16x32_bf16 v[140:143], v[108:111], v[176:179], v[140:143]
	v_mfma_f32_16x16x32_bf16 v[136:139], v[116:119], v[176:179], v[136:139]
	v_mfma_f32_16x16x32_bf16 v[124:127], v[108:111], v[184:187], v[124:127]
	v_mfma_f32_16x16x32_bf16 v[120:123], v[116:119], v[184:187], v[120:123]
	v_mfma_f32_16x16x32_bf16 v[92:95], v[108:111], v[192:195], v[92:95]
	v_mfma_f32_16x16x32_bf16 v[88:91], v[116:119], v[192:195], v[88:91]
	v_mfma_f32_16x16x32_bf16 v[76:79], v[108:111], v[212:215], v[76:79]
	v_mfma_f32_16x16x32_bf16 v[72:75], v[116:119], v[212:215], v[72:75]
	v_mfma_f32_16x16x32_bf16 v[132:135], v[156:159], v[172:175], v[132:135]
	v_mfma_f32_16x16x32_bf16 v[128:131], v[164:167], v[172:175], v[128:131]
	v_mfma_f32_16x16x32_bf16 v[104:107], v[156:159], v[180:183], v[104:107]
	v_mfma_f32_16x16x32_bf16 v[96:99], v[164:167], v[180:183], v[96:99]
	v_mfma_f32_16x16x32_bf16 v[84:87], v[156:159], v[188:191], v[84:87]
	v_mfma_f32_16x16x32_bf16 v[80:83], v[164:167], v[188:191], v[80:83]
	v_mfma_f32_16x16x32_bf16 v[68:71], v[156:159], v[204:207], v[68:71]
	v_mfma_f32_16x16x32_bf16 v[64:67], v[164:167], v[204:207], v[64:67]
	v_mfma_f32_16x16x32_bf16 v[132:135], v[160:163], v[176:179], v[132:135]
	v_mfma_f32_16x16x32_bf16 v[128:131], v[168:171], v[176:179], v[128:131]
	v_mfma_f32_16x16x32_bf16 v[104:107], v[160:163], v[184:187], v[104:107]
	v_mfma_f32_16x16x32_bf16 v[96:99], v[168:171], v[184:187], v[96:99]
	v_mfma_f32_16x16x32_bf16 v[84:87], v[160:163], v[192:195], v[84:87]
	v_mfma_f32_16x16x32_bf16 v[80:83], v[168:171], v[192:195], v[80:83]
	v_mfma_f32_16x16x32_bf16 v[68:71], v[160:163], v[212:215], v[68:71]
	v_mfma_f32_16x16x32_bf16 v[64:67], v[168:171], v[212:215], v[64:67]
	s_setprio 0
	s_barrier
	s_add_i32 s58, s85, s66
	v_lshl_add_u64 v[216:217], s[56:57], 0, v[144:145]
	s_mov_b32 m0, s58
	ds_read_b128 v[172:175], v201 offset:16384
	ds_read_b128 v[176:179], v201 offset:17408
	ds_read_b128 v[180:183], v201 offset:18432
	ds_read_b128 v[184:187], v201 offset:19456
	ds_read_b128 v[188:191], v201 offset:20480
	ds_read_b128 v[192:195], v201 offset:21504
	ds_read_b128 v[204:207], v201 offset:22528
	ds_read_b128 v[212:215], v201 offset:23552
	global_load_lds_dwordx4 v[216:217], off
	s_add_i32 m0, s58, 0x2000
	s_add_u32 s90, s56, 0x40000
	v_lshl_add_u64 v[218:219], s[56:57], 0, v[146:147]
	s_addc_u32 s91, s57, 0
	s_add_i32 s58, s86, s66
	global_load_lds_dwordx4 v[218:219], off
	v_lshl_add_u64 v[220:221], s[90:91], 0, v[144:145]
	s_mov_b32 m0, s58
	v_lshl_add_u64 v[222:223], s[64:65], 0, v[146:147]
	global_load_lds_dwordx4 v[220:221], off
	v_lshl_add_u64 v[220:221], s[90:91], 0, v[146:147]
	s_add_i32 m0, s58, 0x2000
	s_nop 0
	global_load_lds_dwordx4 v[220:221], off
	s_waitcnt vmcnt(6)
	s_waitcnt lgkmcnt(0)
	s_barrier
	s_setprio 1
	v_mfma_f32_16x16x32_bf16 v[60:63], v[100:103], v[172:175], v[60:63]
	v_mfma_f32_16x16x32_bf16 v[56:59], v[112:115], v[172:175], v[56:59]
	v_mfma_f32_16x16x32_bf16 v[44:47], v[100:103], v[180:183], v[44:47]
	v_mfma_f32_16x16x32_bf16 v[40:43], v[112:115], v[180:183], v[40:43]
	v_mfma_f32_16x16x32_bf16 v[28:31], v[100:103], v[188:191], v[28:31]
	v_mfma_f32_16x16x32_bf16 v[24:27], v[112:115], v[188:191], v[24:27]
	v_mfma_f32_16x16x32_bf16 v[12:15], v[100:103], v[204:207], v[12:15]
	v_mfma_f32_16x16x32_bf16 v[8:11], v[112:115], v[204:207], v[8:11]
	v_mfma_f32_16x16x32_bf16 v[60:63], v[108:111], v[176:179], v[60:63]
	v_mfma_f32_16x16x32_bf16 v[56:59], v[116:119], v[176:179], v[56:59]
	v_mfma_f32_16x16x32_bf16 v[44:47], v[108:111], v[184:187], v[44:47]
	v_mfma_f32_16x16x32_bf16 v[40:43], v[116:119], v[184:187], v[40:43]
	v_mfma_f32_16x16x32_bf16 v[28:31], v[108:111], v[192:195], v[28:31]
	v_mfma_f32_16x16x32_bf16 v[24:27], v[116:119], v[192:195], v[24:27]
	v_mfma_f32_16x16x32_bf16 v[12:15], v[108:111], v[212:215], v[12:15]
	v_mfma_f32_16x16x32_bf16 v[8:11], v[116:119], v[212:215], v[8:11]
	v_mfma_f32_16x16x32_bf16 v[52:55], v[156:159], v[172:175], v[52:55]
	v_mfma_f32_16x16x32_bf16 v[48:51], v[164:167], v[172:175], v[48:51]
	v_mfma_f32_16x16x32_bf16 v[36:39], v[156:159], v[180:183], v[36:39]
	v_mfma_f32_16x16x32_bf16 v[32:35], v[164:167], v[180:183], v[32:35]
	v_mfma_f32_16x16x32_bf16 v[20:23], v[156:159], v[188:191], v[20:23]
	v_mfma_f32_16x16x32_bf16 v[16:19], v[164:167], v[188:191], v[16:19]
	v_mfma_f32_16x16x32_bf16 v[4:7], v[156:159], v[204:207], v[4:7]
	v_mfma_f32_16x16x32_bf16 v[0:3], v[164:167], v[204:207], v[0:3]
	v_mfma_f32_16x16x32_bf16 v[52:55], v[160:163], v[176:179], v[52:55]
	v_mfma_f32_16x16x32_bf16 v[48:51], v[168:171], v[176:179], v[48:51]
	v_mfma_f32_16x16x32_bf16 v[36:39], v[160:163], v[184:187], v[36:39]
	v_mfma_f32_16x16x32_bf16 v[32:35], v[168:171], v[184:187], v[32:35]
	v_mfma_f32_16x16x32_bf16 v[20:23], v[160:163], v[192:195], v[20:23]
	v_mfma_f32_16x16x32_bf16 v[16:19], v[168:171], v[192:195], v[16:19]
	v_mfma_f32_16x16x32_bf16 v[4:7], v[160:163], v[212:215], v[4:7]
	v_mfma_f32_16x16x32_bf16 v[0:3], v[168:171], v[212:215], v[0:3]
	s_setprio 0
	s_barrier
	s_add_i32 s58, 0, 0x18000
	s_add_i32 s59, 0, 0x1c000
	v_add_u32_e32 v116, s58, v197
	v_add_u32_e32 v168, s59, v197
	ds_read_b128 v[100:103], v116
	ds_read_b128 v[108:111], v116 offset:1024
	ds_read_b128 v[112:115], v116 offset:2048
	ds_read_b128 v[116:119], v116 offset:3072
	ds_read_b128 v[156:159], v168
	ds_read_b128 v[160:163], v168 offset:1024
	ds_read_b128 v[164:167], v168 offset:2048
	ds_read_b128 v[168:171], v168 offset:3072
	v_lshl_add_u64 v[220:221], s[64:65], 0, v[144:145]
	s_mov_b32 m0, s67
	s_nop 0
	global_load_lds_dwordx4 v[220:221], off
	s_mov_b32 m0, s68
	s_nop 0
	global_load_lds_dwordx4 v[222:223], off
	s_add_u32 s64, s64, 0x40000
	s_addc_u32 s65, s65, 0
	s_mov_b32 m0, s69
	v_lshl_add_u64 v[224:225], s[64:65], 0, v[144:145]
	ds_read_b128 v[172:175], v201 offset:32768
	ds_read_b128 v[176:179], v201 offset:33792
	ds_read_b128 v[180:183], v201 offset:34816
	ds_read_b128 v[184:187], v201 offset:35840
	ds_read_b128 v[188:191], v201 offset:36864
	ds_read_b128 v[192:195], v201 offset:37888
	ds_read_b128 v[204:207], v201 offset:38912
	ds_read_b128 v[212:215], v201 offset:39936
	global_load_lds_dwordx4 v[224:225], off
	v_lshl_add_u64 v[224:225], s[64:65], 0, v[146:147]
	s_mov_b32 m0, s70
	s_nop 0
	global_load_lds_dwordx4 v[224:225], off
	s_waitcnt vmcnt(8)
	s_waitcnt lgkmcnt(0)
	s_barrier
	s_setprio 1
	v_mfma_f32_16x16x32_bf16 v[140:143], v[100:103], v[172:175], v[140:143]
	v_mfma_f32_16x16x32_bf16 v[136:139], v[112:115], v[172:175], v[136:139]
	v_mfma_f32_16x16x32_bf16 v[124:127], v[100:103], v[180:183], v[124:127]
	v_mfma_f32_16x16x32_bf16 v[120:123], v[112:115], v[180:183], v[120:123]
	v_mfma_f32_16x16x32_bf16 v[92:95], v[100:103], v[188:191], v[92:95]
	v_mfma_f32_16x16x32_bf16 v[88:91], v[112:115], v[188:191], v[88:91]
	v_mfma_f32_16x16x32_bf16 v[76:79], v[100:103], v[204:207], v[76:79]
	v_mfma_f32_16x16x32_bf16 v[72:75], v[112:115], v[204:207], v[72:75]
	v_mfma_f32_16x16x32_bf16 v[140:143], v[108:111], v[176:179], v[140:143]
	v_mfma_f32_16x16x32_bf16 v[136:139], v[116:119], v[176:179], v[136:139]
	v_mfma_f32_16x16x32_bf16 v[124:127], v[108:111], v[184:187], v[124:127]
	v_mfma_f32_16x16x32_bf16 v[120:123], v[116:119], v[184:187], v[120:123]
	v_mfma_f32_16x16x32_bf16 v[92:95], v[108:111], v[192:195], v[92:95]
	v_mfma_f32_16x16x32_bf16 v[88:91], v[116:119], v[192:195], v[88:91]
	v_mfma_f32_16x16x32_bf16 v[76:79], v[108:111], v[212:215], v[76:79]
	v_mfma_f32_16x16x32_bf16 v[72:75], v[116:119], v[212:215], v[72:75]
	v_mfma_f32_16x16x32_bf16 v[132:135], v[156:159], v[172:175], v[132:135]
	v_mfma_f32_16x16x32_bf16 v[128:131], v[164:167], v[172:175], v[128:131]
	v_mfma_f32_16x16x32_bf16 v[104:107], v[156:159], v[180:183], v[104:107]
	v_mfma_f32_16x16x32_bf16 v[96:99], v[164:167], v[180:183], v[96:99]
	v_mfma_f32_16x16x32_bf16 v[84:87], v[156:159], v[188:191], v[84:87]
	v_mfma_f32_16x16x32_bf16 v[80:83], v[164:167], v[188:191], v[80:83]
	v_mfma_f32_16x16x32_bf16 v[68:71], v[156:159], v[204:207], v[68:71]
	v_mfma_f32_16x16x32_bf16 v[64:67], v[164:167], v[204:207], v[64:67]
	v_mfma_f32_16x16x32_bf16 v[132:135], v[160:163], v[176:179], v[132:135]
	v_mfma_f32_16x16x32_bf16 v[128:131], v[168:171], v[176:179], v[128:131]
	v_mfma_f32_16x16x32_bf16 v[104:107], v[160:163], v[184:187], v[104:107]
	v_mfma_f32_16x16x32_bf16 v[96:99], v[168:171], v[184:187], v[96:99]
	v_mfma_f32_16x16x32_bf16 v[84:87], v[160:163], v[192:195], v[84:87]
	v_mfma_f32_16x16x32_bf16 v[80:83], v[168:171], v[192:195], v[80:83]
	v_mfma_f32_16x16x32_bf16 v[68:71], v[160:163], v[212:215], v[68:71]
	v_mfma_f32_16x16x32_bf16 v[64:67], v[168:171], v[212:215], v[64:67]
	s_setprio 0
	s_barrier
	s_add_i32 s58, s58, s66
	v_lshl_add_u64 v[216:217], v[216:217], 0, s[36:37]
	s_mov_b32 m0, s58
	ds_read_b128 v[172:175], v201 offset:49152
	ds_read_b128 v[176:179], v201 offset:50176
	ds_read_b128 v[180:183], v201 offset:51200
	ds_read_b128 v[184:187], v201 offset:52224
	ds_read_b128 v[188:191], v201 offset:53248
	ds_read_b128 v[192:195], v201 offset:54272
	ds_read_b128 v[204:207], v201 offset:55296
	ds_read_b128 v[212:215], v201 offset:56320
	global_load_lds_dwordx4 v[216:217], off
	s_add_i32 m0, s58, 0x2000
	s_add_u32 s56, s56, 0x40080
	v_lshl_add_u64 v[216:217], v[218:219], 0, s[36:37]
	s_addc_u32 s57, s57, 0
	s_add_i32 s58, s59, s66
	global_load_lds_dwordx4 v[216:217], off
	v_lshl_add_u64 v[216:217], s[56:57], 0, v[144:145]
	s_mov_b32 m0, s58
	s_nop 0
	global_load_lds_dwordx4 v[216:217], off
	v_lshl_add_u64 v[216:217], s[56:57], 0, v[146:147]
	s_add_i32 m0, s58, 0x2000
	s_nop 0
	global_load_lds_dwordx4 v[216:217], off
	v_lshl_add_u64 v[216:217], v[220:221], 0, s[36:37]
	s_mov_b32 m0, s80
	s_nop 0
	global_load_lds_dwordx4 v[216:217], off
	v_lshl_add_u64 v[216:217], v[222:223], 0, s[36:37]
	s_mov_b32 m0, s81
	s_nop 0
	global_load_lds_dwordx4 v[216:217], off
	s_waitcnt vmcnt(6)
	s_waitcnt lgkmcnt(0)
	s_barrier
	s_setprio 1
	v_mfma_f32_16x16x32_bf16 v[60:63], v[100:103], v[172:175], v[60:63]
	v_mfma_f32_16x16x32_bf16 v[56:59], v[112:115], v[172:175], v[56:59]
	v_mfma_f32_16x16x32_bf16 v[44:47], v[100:103], v[180:183], v[44:47]
	v_mfma_f32_16x16x32_bf16 v[40:43], v[112:115], v[180:183], v[40:43]
	v_mfma_f32_16x16x32_bf16 v[28:31], v[100:103], v[188:191], v[28:31]
	v_mfma_f32_16x16x32_bf16 v[24:27], v[112:115], v[188:191], v[24:27]
	v_mfma_f32_16x16x32_bf16 v[12:15], v[100:103], v[204:207], v[12:15]
	v_mfma_f32_16x16x32_bf16 v[8:11], v[112:115], v[204:207], v[8:11]
	v_mfma_f32_16x16x32_bf16 v[60:63], v[108:111], v[176:179], v[60:63]
	v_mfma_f32_16x16x32_bf16 v[56:59], v[116:119], v[176:179], v[56:59]
	v_mfma_f32_16x16x32_bf16 v[44:47], v[108:111], v[184:187], v[44:47]
	v_mfma_f32_16x16x32_bf16 v[40:43], v[116:119], v[184:187], v[40:43]
	v_mfma_f32_16x16x32_bf16 v[28:31], v[108:111], v[192:195], v[28:31]
	v_mfma_f32_16x16x32_bf16 v[24:27], v[116:119], v[192:195], v[24:27]
	v_mfma_f32_16x16x32_bf16 v[12:15], v[108:111], v[212:215], v[12:15]
	v_mfma_f32_16x16x32_bf16 v[8:11], v[116:119], v[212:215], v[8:11]
	v_mfma_f32_16x16x32_bf16 v[52:55], v[156:159], v[172:175], v[52:55]
	v_mfma_f32_16x16x32_bf16 v[48:51], v[164:167], v[172:175], v[48:51]
	v_mfma_f32_16x16x32_bf16 v[36:39], v[156:159], v[180:183], v[36:39]
	v_mfma_f32_16x16x32_bf16 v[32:35], v[164:167], v[180:183], v[32:35]
	v_mfma_f32_16x16x32_bf16 v[20:23], v[156:159], v[188:191], v[20:23]
	v_mfma_f32_16x16x32_bf16 v[16:19], v[164:167], v[188:191], v[16:19]
	v_mfma_f32_16x16x32_bf16 v[4:7], v[156:159], v[204:207], v[4:7]
	v_mfma_f32_16x16x32_bf16 v[0:3], v[164:167], v[204:207], v[0:3]
	v_mfma_f32_16x16x32_bf16 v[52:55], v[160:163], v[176:179], v[52:55]
	v_mfma_f32_16x16x32_bf16 v[48:51], v[168:171], v[176:179], v[48:51]
	v_mfma_f32_16x16x32_bf16 v[36:39], v[160:163], v[184:187], v[36:39]
	v_mfma_f32_16x16x32_bf16 v[32:35], v[168:171], v[184:187], v[32:35]
	v_mfma_f32_16x16x32_bf16 v[20:23], v[160:163], v[192:195], v[20:23]
	v_mfma_f32_16x16x32_bf16 v[16:19], v[168:171], v[192:195], v[16:19]
	v_mfma_f32_16x16x32_bf16 v[4:7], v[160:163], v[212:215], v[4:7]
	v_mfma_f32_16x16x32_bf16 v[0:3], v[168:171], v[212:215], v[0:3]
	s_setprio 0
	s_barrier
	s_add_i32 s88, s88, 2
	s_add_u32 s54, s54, 0x100
	s_addc_u32 s55, s55, 0
	s_add_u32 s87, s87, 0x100
	s_addc_u32 s33, s33, 0
	s_cmp_gt_u32 s88, 13
	s_cbranch_scc0 .LBB0_544
	s_and_b64 vcc, exec, s[38:39]
	s_cbranch_vccz .LBB0_547
	s_barrier

.LBB0_639:
	ds_read_b128 v[144:147], v151
	ds_read_b128 v[154:157], v151 offset:1024
	ds_read_b128 v[158:161], v151 offset:2048
	ds_read_b128 v[162:165], v151 offset:3072
	ds_read_b128 v[166:169], v152
	ds_read_b128 v[170:173], v152 offset:1024
	ds_read_b128 v[174:177], v152 offset:2048
	ds_read_b128 v[178:181], v152 offset:3072
	s_add_u32 s40, s38, 0xfffc0080
	s_addc_u32 s41, s39, -1
	s_cmp_eq_u32 s68, 12
	s_cselect_b32 s43, s21, s41
	s_cselect_b32 s42, s65, s40
	s_cselect_b32 s41, s17, s33
	s_cselect_b32 s40, s66, s67
	v_lshl_add_u64 v[206:207], s[38:39], 0, v[136:137]
	s_add_i32 m0, s37, 0xc000
	ds_read_b128 v[182:185], v153
	ds_read_b128 v[186:189], v153 offset:1024
	ds_read_b128 v[190:193], v153 offset:2048
	ds_read_b128 v[194:197], v153 offset:3072
	ds_read_b128 v[198:201], v153 offset:4096
	ds_read_b128 v[202:205], v153 offset:5120
	ds_read_b128 v[212:215], v153 offset:6144
	ds_read_b128 v[216:219], v153 offset:7168
	global_load_lds_dwordx4 v[206:207], off
	v_lshl_add_u64 v[206:207], s[38:39], 0, v[138:139]
	s_add_i32 m0, s37, 0xe000
	s_nop 0
	global_load_lds_dwordx4 v[206:207], off
	s_waitcnt vmcnt(8)
	s_waitcnt lgkmcnt(0)
	s_barrier
	s_setprio 1
	v_mfma_f32_16x16x32_bf16 v[124:127], v[144:147], v[182:185], v[124:127]
	v_mfma_f32_16x16x32_bf16 v[116:119], v[158:161], v[182:185], v[116:119]
	v_mfma_f32_16x16x32_bf16 v[108:111], v[144:147], v[190:193], v[108:111]
	v_mfma_f32_16x16x32_bf16 v[100:103], v[158:161], v[190:193], v[100:103]
	v_mfma_f32_16x16x32_bf16 v[92:95], v[144:147], v[198:201], v[92:95]
	v_mfma_f32_16x16x32_bf16 v[84:87], v[158:161], v[198:201], v[84:87]
	v_mfma_f32_16x16x32_bf16 v[76:79], v[144:147], v[212:215], v[76:79]
	v_mfma_f32_16x16x32_bf16 v[68:71], v[158:161], v[212:215], v[68:71]
	v_mfma_f32_16x16x32_bf16 v[124:127], v[154:157], v[186:189], v[124:127]
	v_mfma_f32_16x16x32_bf16 v[116:119], v[162:165], v[186:189], v[116:119]
	v_mfma_f32_16x16x32_bf16 v[108:111], v[154:157], v[194:197], v[108:111]
	v_mfma_f32_16x16x32_bf16 v[100:103], v[162:165], v[194:197], v[100:103]
	v_mfma_f32_16x16x32_bf16 v[92:95], v[154:157], v[202:205], v[92:95]
	v_mfma_f32_16x16x32_bf16 v[84:87], v[162:165], v[202:205], v[84:87]
	v_mfma_f32_16x16x32_bf16 v[76:79], v[154:157], v[216:219], v[76:79]
	v_mfma_f32_16x16x32_bf16 v[68:71], v[162:165], v[216:219], v[68:71]
	v_mfma_f32_16x16x32_bf16 v[120:123], v[166:169], v[182:185], v[120:123]
	v_mfma_f32_16x16x32_bf16 v[112:115], v[174:177], v[182:185], v[112:115]
	v_mfma_f32_16x16x32_bf16 v[104:107], v[166:169], v[190:193], v[104:107]
	v_mfma_f32_16x16x32_bf16 v[96:99], v[174:177], v[190:193], v[96:99]
	v_mfma_f32_16x16x32_bf16 v[88:91], v[166:169], v[198:201], v[88:91]
	v_mfma_f32_16x16x32_bf16 v[80:83], v[174:177], v[198:201], v[80:83]
	v_mfma_f32_16x16x32_bf16 v[72:75], v[166:169], v[212:215], v[72:75]
	v_mfma_f32_16x16x32_bf16 v[64:67], v[174:177], v[212:215], v[64:67]
	v_mfma_f32_16x16x32_bf16 v[120:123], v[170:173], v[186:189], v[120:123]
	v_mfma_f32_16x16x32_bf16 v[112:115], v[178:181], v[186:189], v[112:115]
	v_mfma_f32_16x16x32_bf16 v[104:107], v[170:173], v[194:197], v[104:107]
	v_mfma_f32_16x16x32_bf16 v[96:99], v[178:181], v[194:197], v[96:99]
	v_mfma_f32_16x16x32_bf16 v[88:91], v[170:173], v[202:205], v[88:91]
	v_mfma_f32_16x16x32_bf16 v[80:83], v[178:181], v[202:205], v[80:83]
	v_mfma_f32_16x16x32_bf16 v[72:75], v[170:173], v[216:219], v[72:75]
	v_mfma_f32_16x16x32_bf16 v[64:67], v[178:181], v[216:219], v[64:67]
	s_setprio 0
	s_barrier
	s_add_i32 s58, s55, s44
	v_lshl_add_u64 v[206:207], s[40:41], 0, v[132:133]
	s_mov_b32 m0, s58
	ds_read_b128 v[182:185], v153 offset:16384
	ds_read_b128 v[186:189], v153 offset:17408
	ds_read_b128 v[190:193], v153 offset:18432
	ds_read_b128 v[194:197], v153 offset:19456
	ds_read_b128 v[198:201], v153 offset:20480
	ds_read_b128 v[202:205], v153 offset:21504
	ds_read_b128 v[212:215], v153 offset:22528
	ds_read_b128 v[216:219], v153 offset:23552
	global_load_lds_dwordx4 v[206:207], off
	s_add_i32 m0, s58, 0x2000
	s_add_u32 s70, s40, 0x40000
	v_lshl_add_u64 v[220:221], s[40:41], 0, v[128:129]
	s_addc_u32 s71, s41, 0
	s_add_i32 s58, s56, s44
	global_load_lds_dwordx4 v[220:221], off
	v_lshl_add_u64 v[222:223], s[70:71], 0, v[132:133]
	s_mov_b32 m0, s58
	v_lshl_add_u64 v[224:225], s[42:43], 0, v[130:131]
	global_load_lds_dwordx4 v[222:223], off
	v_lshl_add_u64 v[222:223], s[70:71], 0, v[128:129]
	s_add_i32 m0, s58, 0x2000
	s_nop 0
	global_load_lds_dwordx4 v[222:223], off
	s_waitcnt vmcnt(6)
	s_waitcnt lgkmcnt(0)
	s_barrier
	s_setprio 1
	v_mfma_f32_16x16x32_bf16 v[60:63], v[144:147], v[182:185], v[60:63]
	v_mfma_f32_16x16x32_bf16 v[52:55], v[158:161], v[182:185], v[52:55]
	v_mfma_f32_16x16x32_bf16 v[44:47], v[144:147], v[190:193], v[44:47]
	v_mfma_f32_16x16x32_bf16 v[36:39], v[158:161], v[190:193], v[36:39]
	v_mfma_f32_16x16x32_bf16 v[28:31], v[144:147], v[198:201], v[28:31]
	v_mfma_f32_16x16x32_bf16 v[20:23], v[158:161], v[198:201], v[20:23]
	v_mfma_f32_16x16x32_bf16 v[12:15], v[144:147], v[212:215], v[12:15]
	v_mfma_f32_16x16x32_bf16 v[4:7], v[158:161], v[212:215], v[4:7]
	v_mfma_f32_16x16x32_bf16 v[60:63], v[154:157], v[186:189], v[60:63]
	v_mfma_f32_16x16x32_bf16 v[52:55], v[162:165], v[186:189], v[52:55]
	v_mfma_f32_16x16x32_bf16 v[44:47], v[154:157], v[194:197], v[44:47]
	v_mfma_f32_16x16x32_bf16 v[36:39], v[162:165], v[194:197], v[36:39]
	v_mfma_f32_16x16x32_bf16 v[28:31], v[154:157], v[202:205], v[28:31]
	v_mfma_f32_16x16x32_bf16 v[20:23], v[162:165], v[202:205], v[20:23]
	v_mfma_f32_16x16x32_bf16 v[12:15], v[154:157], v[216:219], v[12:15]
	v_mfma_f32_16x16x32_bf16 v[4:7], v[162:165], v[216:219], v[4:7]
	v_mfma_f32_16x16x32_bf16 v[56:59], v[166:169], v[182:185], v[56:59]
	v_mfma_f32_16x16x32_bf16 v[48:51], v[174:177], v[182:185], v[48:51]
	v_mfma_f32_16x16x32_bf16 v[40:43], v[166:169], v[190:193], v[40:43]
	v_mfma_f32_16x16x32_bf16 v[32:35], v[174:177], v[190:193], v[32:35]
	v_mfma_f32_16x16x32_bf16 v[24:27], v[166:169], v[198:201], v[24:27]
	v_mfma_f32_16x16x32_bf16 v[16:19], v[174:177], v[198:201], v[16:19]
	v_mfma_f32_16x16x32_bf16 v[8:11], v[166:169], v[212:215], v[8:11]
	v_mfma_f32_16x16x32_bf16 v[0:3], v[174:177], v[212:215], v[0:3]
	v_mfma_f32_16x16x32_bf16 v[56:59], v[170:173], v[186:189], v[56:59]
	v_mfma_f32_16x16x32_bf16 v[48:51], v[178:181], v[186:189], v[48:51]
	v_mfma_f32_16x16x32_bf16 v[40:43], v[170:173], v[194:197], v[40:43]
	v_mfma_f32_16x16x32_bf16 v[32:35], v[178:181], v[194:197], v[32:35]
	v_mfma_f32_16x16x32_bf16 v[24:27], v[170:173], v[202:205], v[24:27]
	v_mfma_f32_16x16x32_bf16 v[16:19], v[178:181], v[202:205], v[16:19]
	v_mfma_f32_16x16x32_bf16 v[8:11], v[170:173], v[216:219], v[8:11]
	v_mfma_f32_16x16x32_bf16 v[0:3], v[178:181], v[216:219], v[0:3]
	s_setprio 0
	s_barrier
	s_add_i32 s58, 0, 0x18000
	s_add_i32 s59, 0, 0x1c000
	v_add_u32_e32 v162, s58, v149
	v_add_u32_e32 v178, s59, v149
	ds_read_b128 v[144:147], v162
	ds_read_b128 v[154:157], v162 offset:1024
	ds_read_b128 v[158:161], v162 offset:2048
	ds_read_b128 v[162:165], v162 offset:3072
	ds_read_b128 v[166:169], v178
	ds_read_b128 v[170:173], v178 offset:1024
	ds_read_b128 v[174:177], v178 offset:2048
	ds_read_b128 v[178:181], v178 offset:3072
	v_lshl_add_u64 v[222:223], s[42:43], 0, v[134:135]
	s_mov_b32 m0, s37
	s_nop 0
	global_load_lds_dwordx4 v[222:223], off
	s_mov_b32 m0, s47
	s_nop 0
	global_load_lds_dwordx4 v[224:225], off
	s_add_u32 s42, s42, 0x40000
	s_addc_u32 s43, s43, 0
	s_mov_b32 m0, s48
	v_lshl_add_u64 v[226:227], s[42:43], 0, v[134:135]
	ds_read_b128 v[182:185], v153 offset:32768
	ds_read_b128 v[186:189], v153 offset:33792
	ds_read_b128 v[190:193], v153 offset:34816
	ds_read_b128 v[194:197], v153 offset:35840
	ds_read_b128 v[198:201], v153 offset:36864
	ds_read_b128 v[202:205], v153 offset:37888
	ds_read_b128 v[212:215], v153 offset:38912
	ds_read_b128 v[216:219], v153 offset:39936
	global_load_lds_dwordx4 v[226:227], off
	v_lshl_add_u64 v[226:227], s[42:43], 0, v[130:131]
	s_mov_b32 m0, s49
	s_nop 0
	global_load_lds_dwordx4 v[226:227], off
	s_waitcnt vmcnt(8)
	s_waitcnt lgkmcnt(0)
	s_barrier
	s_setprio 1
	v_mfma_f32_16x16x32_bf16 v[124:127], v[144:147], v[182:185], v[124:127]
	v_mfma_f32_16x16x32_bf16 v[116:119], v[158:161], v[182:185], v[116:119]
	v_mfma_f32_16x16x32_bf16 v[108:111], v[144:147], v[190:193], v[108:111]
	v_mfma_f32_16x16x32_bf16 v[100:103], v[158:161], v[190:193], v[100:103]
	v_mfma_f32_16x16x32_bf16 v[92:95], v[144:147], v[198:201], v[92:95]
	v_mfma_f32_16x16x32_bf16 v[84:87], v[158:161], v[198:201], v[84:87]
	v_mfma_f32_16x16x32_bf16 v[76:79], v[144:147], v[212:215], v[76:79]
	v_mfma_f32_16x16x32_bf16 v[68:71], v[158:161], v[212:215], v[68:71]
	v_mfma_f32_16x16x32_bf16 v[124:127], v[154:157], v[186:189], v[124:127]
	v_mfma_f32_16x16x32_bf16 v[116:119], v[162:165], v[186:189], v[116:119]
	v_mfma_f32_16x16x32_bf16 v[108:111], v[154:157], v[194:197], v[108:111]
	v_mfma_f32_16x16x32_bf16 v[100:103], v[162:165], v[194:197], v[100:103]
	v_mfma_f32_16x16x32_bf16 v[92:95], v[154:157], v[202:205], v[92:95]
	v_mfma_f32_16x16x32_bf16 v[84:87], v[162:165], v[202:205], v[84:87]
	v_mfma_f32_16x16x32_bf16 v[76:79], v[154:157], v[216:219], v[76:79]
	v_mfma_f32_16x16x32_bf16 v[68:71], v[162:165], v[216:219], v[68:71]
	v_mfma_f32_16x16x32_bf16 v[120:123], v[166:169], v[182:185], v[120:123]
	v_mfma_f32_16x16x32_bf16 v[112:115], v[174:177], v[182:185], v[112:115]
	v_mfma_f32_16x16x32_bf16 v[104:107], v[166:169], v[190:193], v[104:107]
	v_mfma_f32_16x16x32_bf16 v[96:99], v[174:177], v[190:193], v[96:99]
	v_mfma_f32_16x16x32_bf16 v[88:91], v[166:169], v[198:201], v[88:91]
	v_mfma_f32_16x16x32_bf16 v[80:83], v[174:177], v[198:201], v[80:83]
	v_mfma_f32_16x16x32_bf16 v[72:75], v[166:169], v[212:215], v[72:75]
	v_mfma_f32_16x16x32_bf16 v[64:67], v[174:177], v[212:215], v[64:67]
	v_mfma_f32_16x16x32_bf16 v[120:123], v[170:173], v[186:189], v[120:123]
	v_mfma_f32_16x16x32_bf16 v[112:115], v[178:181], v[186:189], v[112:115]
	v_mfma_f32_16x16x32_bf16 v[104:107], v[170:173], v[194:197], v[104:107]
	v_mfma_f32_16x16x32_bf16 v[96:99], v[178:181], v[194:197], v[96:99]
	v_mfma_f32_16x16x32_bf16 v[88:91], v[170:173], v[202:205], v[88:91]
	v_mfma_f32_16x16x32_bf16 v[80:83], v[178:181], v[202:205], v[80:83]
	v_mfma_f32_16x16x32_bf16 v[72:75], v[170:173], v[216:219], v[72:75]
	v_mfma_f32_16x16x32_bf16 v[64:67], v[178:181], v[216:219], v[64:67]
	s_setprio 0
	s_barrier
	s_add_i32 s42, s58, s44
	v_lshl_add_u64 v[206:207], v[206:207], 0, s[6:7]
	s_mov_b32 m0, s42
	ds_read_b128 v[182:185], v153 offset:49152
	ds_read_b128 v[186:189], v153 offset:50176
	ds_read_b128 v[190:193], v153 offset:51200
	ds_read_b128 v[194:197], v153 offset:52224
	ds_read_b128 v[198:201], v153 offset:53248
	ds_read_b128 v[202:205], v153 offset:54272
	ds_read_b128 v[212:215], v153 offset:55296
	ds_read_b128 v[216:219], v153 offset:56320
	global_load_lds_dwordx4 v[206:207], off
	s_add_i32 m0, s42, 0x2000
	s_add_u32 s40, s40, 0x40080
	v_lshl_add_u64 v[206:207], v[220:221], 0, s[6:7]
	s_addc_u32 s41, s41, 0
	s_add_i32 s42, s59, s44
	global_load_lds_dwordx4 v[206:207], off
	v_lshl_add_u64 v[206:207], s[40:41], 0, v[132:133]
	s_mov_b32 m0, s42
	s_nop 0
	global_load_lds_dwordx4 v[206:207], off
	v_lshl_add_u64 v[206:207], s[40:41], 0, v[128:129]
	s_add_i32 m0, s42, 0x2000
	s_nop 0
	global_load_lds_dwordx4 v[206:207], off
	v_lshl_add_u64 v[206:207], v[222:223], 0, s[6:7]
	s_mov_b32 m0, s51
	s_nop 0
	global_load_lds_dwordx4 v[206:207], off
	v_lshl_add_u64 v[206:207], v[224:225], 0, s[6:7]
	s_mov_b32 m0, s52
	s_nop 0
	global_load_lds_dwordx4 v[206:207], off
	s_waitcnt vmcnt(6)
	s_waitcnt lgkmcnt(0)
	s_barrier
	s_setprio 1
	v_mfma_f32_16x16x32_bf16 v[60:63], v[144:147], v[182:185], v[60:63]
	v_mfma_f32_16x16x32_bf16 v[52:55], v[158:161], v[182:185], v[52:55]
	v_mfma_f32_16x16x32_bf16 v[44:47], v[144:147], v[190:193], v[44:47]
	v_mfma_f32_16x16x32_bf16 v[36:39], v[158:161], v[190:193], v[36:39]
	v_mfma_f32_16x16x32_bf16 v[28:31], v[144:147], v[198:201], v[28:31]
	v_mfma_f32_16x16x32_bf16 v[20:23], v[158:161], v[198:201], v[20:23]
	v_mfma_f32_16x16x32_bf16 v[12:15], v[144:147], v[212:215], v[12:15]
	v_mfma_f32_16x16x32_bf16 v[4:7], v[158:161], v[212:215], v[4:7]
	v_mfma_f32_16x16x32_bf16 v[60:63], v[154:157], v[186:189], v[60:63]
	v_mfma_f32_16x16x32_bf16 v[52:55], v[162:165], v[186:189], v[52:55]
	v_mfma_f32_16x16x32_bf16 v[44:47], v[154:157], v[194:197], v[44:47]
	v_mfma_f32_16x16x32_bf16 v[36:39], v[162:165], v[194:197], v[36:39]
	v_mfma_f32_16x16x32_bf16 v[28:31], v[154:157], v[202:205], v[28:31]
	v_mfma_f32_16x16x32_bf16 v[20:23], v[162:165], v[202:205], v[20:23]
	v_mfma_f32_16x16x32_bf16 v[12:15], v[154:157], v[216:219], v[12:15]
	v_mfma_f32_16x16x32_bf16 v[4:7], v[162:165], v[216:219], v[4:7]
	v_mfma_f32_16x16x32_bf16 v[56:59], v[166:169], v[182:185], v[56:59]
	v_mfma_f32_16x16x32_bf16 v[48:51], v[174:177], v[182:185], v[48:51]
	v_mfma_f32_16x16x32_bf16 v[40:43], v[166:169], v[190:193], v[40:43]
	v_mfma_f32_16x16x32_bf16 v[32:35], v[174:177], v[190:193], v[32:35]
	v_mfma_f32_16x16x32_bf16 v[24:27], v[166:169], v[198:201], v[24:27]
	v_mfma_f32_16x16x32_bf16 v[16:19], v[174:177], v[198:201], v[16:19]
	v_mfma_f32_16x16x32_bf16 v[8:11], v[166:169], v[212:215], v[8:11]
	v_mfma_f32_16x16x32_bf16 v[0:3], v[174:177], v[212:215], v[0:3]
	v_mfma_f32_16x16x32_bf16 v[56:59], v[170:173], v[186:189], v[56:59]
	v_mfma_f32_16x16x32_bf16 v[48:51], v[178:181], v[186:189], v[48:51]
	v_mfma_f32_16x16x32_bf16 v[40:43], v[170:173], v[194:197], v[40:43]
	v_mfma_f32_16x16x32_bf16 v[32:35], v[178:181], v[194:197], v[32:35]
	v_mfma_f32_16x16x32_bf16 v[24:27], v[170:173], v[202:205], v[24:27]
	v_mfma_f32_16x16x32_bf16 v[16:19], v[178:181], v[202:205], v[16:19]
	v_mfma_f32_16x16x32_bf16 v[8:11], v[170:173], v[216:219], v[8:11]
	v_mfma_f32_16x16x32_bf16 v[0:3], v[178:181], v[216:219], v[0:3]
	s_setprio 0
	s_barrier
	s_add_i32 s68, s68, 2
	s_add_u32 s38, s38, 0x100
	s_addc_u32 s39, s39, 0
	s_add_u32 s67, s67, 0x100
	s_addc_u32 s33, s33, 0
	s_cmp_gt_u32 s68, 13
	s_cbranch_scc0 .LBB0_639
	s_and_b64 vcc, exec, s[8:9]
	s_cbranch_vccz .LBB0_642
	s_barrier

.LBB0_722:
	ds_read_b128 v[96:99], v185
	ds_read_b128 v[100:103], v185 offset:1024
	ds_read_b128 v[104:107], v185 offset:2048
	ds_read_b128 v[108:111], v185 offset:3072
	ds_read_b128 v[156:159], v186
	ds_read_b128 v[160:163], v186 offset:1024
	ds_read_b128 v[164:167], v186 offset:2048
	ds_read_b128 v[168:171], v186 offset:3072
	s_add_u32 s28, s26, 0x100
	s_addc_u32 s29, s27, 0
	s_cmp_eq_u32 s57, 40
	s_cselect_b32 s37, s7, s29
	s_cselect_b32 s36, s6, s28
	s_cselect_b32 s35, s23, s56
	s_cselect_b32 s34, s22, s55
	v_lshl_add_u64 v[180:181], s[26:27], 0, v[148:149]
	s_add_i32 m0, s15, 0xc000
	ds_read_b128 v[172:175], v187
	ds_read_b128 v[176:179], v187 offset:1024
	ds_read_b128 v[190:193], v187 offset:2048
	ds_read_b128 v[194:197], v187 offset:3072
	ds_read_b128 v[198:201], v187 offset:4096
	ds_read_b128 v[202:205], v187 offset:5120
	ds_read_b128 v[206:209], v187 offset:6144
	ds_read_b128 v[212:215], v187 offset:7168
	global_load_lds_dwordx4 v[180:181], off
	v_lshl_add_u64 v[180:181], s[26:27], 0, v[150:151]
	s_add_i32 m0, s15, 0xe000
	s_nop 0
	global_load_lds_dwordx4 v[180:181], off
	s_waitcnt vmcnt(8)
	s_waitcnt lgkmcnt(0)
	s_barrier
	s_setprio 1
	v_mfma_f32_16x16x32_bf16 v[140:143], v[96:99], v[172:175], v[140:143]
	v_mfma_f32_16x16x32_bf16 v[136:139], v[104:107], v[172:175], v[136:139]
	v_mfma_f32_16x16x32_bf16 v[124:127], v[96:99], v[190:193], v[124:127]
	v_mfma_f32_16x16x32_bf16 v[120:123], v[104:107], v[190:193], v[120:123]
	v_mfma_f32_16x16x32_bf16 v[92:95], v[96:99], v[198:201], v[92:95]
	v_mfma_f32_16x16x32_bf16 v[88:91], v[104:107], v[198:201], v[88:91]
	v_mfma_f32_16x16x32_bf16 v[76:79], v[96:99], v[206:209], v[76:79]
	v_mfma_f32_16x16x32_bf16 v[72:75], v[104:107], v[206:209], v[72:75]
	v_mfma_f32_16x16x32_bf16 v[140:143], v[100:103], v[176:179], v[140:143]
	v_mfma_f32_16x16x32_bf16 v[136:139], v[108:111], v[176:179], v[136:139]
	v_mfma_f32_16x16x32_bf16 v[124:127], v[100:103], v[194:197], v[124:127]
	v_mfma_f32_16x16x32_bf16 v[120:123], v[108:111], v[194:197], v[120:123]
	v_mfma_f32_16x16x32_bf16 v[92:95], v[100:103], v[202:205], v[92:95]
	v_mfma_f32_16x16x32_bf16 v[88:91], v[108:111], v[202:205], v[88:91]
	v_mfma_f32_16x16x32_bf16 v[76:79], v[100:103], v[212:215], v[76:79]
	v_mfma_f32_16x16x32_bf16 v[72:75], v[108:111], v[212:215], v[72:75]
	v_mfma_f32_16x16x32_bf16 v[132:135], v[156:159], v[172:175], v[132:135]
	v_mfma_f32_16x16x32_bf16 v[128:131], v[164:167], v[172:175], v[128:131]
	v_mfma_f32_16x16x32_bf16 v[116:119], v[156:159], v[190:193], v[116:119]
	v_mfma_f32_16x16x32_bf16 v[112:115], v[164:167], v[190:193], v[112:115]
	v_mfma_f32_16x16x32_bf16 v[84:87], v[156:159], v[198:201], v[84:87]
	v_mfma_f32_16x16x32_bf16 v[80:83], v[164:167], v[198:201], v[80:83]
	v_mfma_f32_16x16x32_bf16 v[68:71], v[156:159], v[206:209], v[68:71]
	v_mfma_f32_16x16x32_bf16 v[64:67], v[164:167], v[206:209], v[64:67]
	v_mfma_f32_16x16x32_bf16 v[132:135], v[160:163], v[176:179], v[132:135]
	v_mfma_f32_16x16x32_bf16 v[128:131], v[168:171], v[176:179], v[128:131]
	v_mfma_f32_16x16x32_bf16 v[116:119], v[160:163], v[194:197], v[116:119]
	v_mfma_f32_16x16x32_bf16 v[112:115], v[168:171], v[194:197], v[112:115]
	v_mfma_f32_16x16x32_bf16 v[84:87], v[160:163], v[202:205], v[84:87]
	v_mfma_f32_16x16x32_bf16 v[80:83], v[168:171], v[202:205], v[80:83]
	v_mfma_f32_16x16x32_bf16 v[68:71], v[160:163], v[212:215], v[68:71]
	v_mfma_f32_16x16x32_bf16 v[64:67], v[168:171], v[212:215], v[64:67]
	s_setprio 0
	s_barrier
	s_add_i32 s26, s49, s3
	v_lshl_add_u64 v[180:181], s[34:35], 0, v[144:145]
	s_mov_b32 m0, s26
	ds_read_b128 v[172:175], v187 offset:16384
	ds_read_b128 v[176:179], v187 offset:17408
	ds_read_b128 v[190:193], v187 offset:18432
	ds_read_b128 v[194:197], v187 offset:19456
	ds_read_b128 v[198:201], v187 offset:20480
	ds_read_b128 v[202:205], v187 offset:21504
	ds_read_b128 v[206:209], v187 offset:22528
	ds_read_b128 v[212:215], v187 offset:23552
	global_load_lds_dwordx4 v[180:181], off
	s_add_i32 m0, s26, 0x2000
	s_add_u32 s26, s34, 0xb0000
	v_lshl_add_u64 v[216:217], s[34:35], 0, v[146:147]
	s_addc_u32 s27, s35, 0
	s_add_i32 s58, s50, s3
	global_load_lds_dwordx4 v[216:217], off
	v_lshl_add_u64 v[218:219], s[26:27], 0, v[144:145]
	s_mov_b32 m0, s58
	v_lshl_add_u64 v[220:221], s[36:37], 0, v[146:147]
	global_load_lds_dwordx4 v[218:219], off
	v_lshl_add_u64 v[218:219], s[26:27], 0, v[146:147]
	s_add_i32 m0, s58, 0x2000
	s_nop 0
	global_load_lds_dwordx4 v[218:219], off
	s_waitcnt vmcnt(6)
	s_waitcnt lgkmcnt(0)
	s_barrier
	s_setprio 1
	v_mfma_f32_16x16x32_bf16 v[60:63], v[96:99], v[172:175], v[60:63]
	v_mfma_f32_16x16x32_bf16 v[56:59], v[104:107], v[172:175], v[56:59]
	v_mfma_f32_16x16x32_bf16 v[44:47], v[96:99], v[190:193], v[44:47]
	v_mfma_f32_16x16x32_bf16 v[40:43], v[104:107], v[190:193], v[40:43]
	v_mfma_f32_16x16x32_bf16 v[28:31], v[96:99], v[198:201], v[28:31]
	v_mfma_f32_16x16x32_bf16 v[24:27], v[104:107], v[198:201], v[24:27]
	v_mfma_f32_16x16x32_bf16 v[12:15], v[96:99], v[206:209], v[12:15]
	v_mfma_f32_16x16x32_bf16 v[8:11], v[104:107], v[206:209], v[8:11]
	v_mfma_f32_16x16x32_bf16 v[60:63], v[100:103], v[176:179], v[60:63]
	v_mfma_f32_16x16x32_bf16 v[56:59], v[108:111], v[176:179], v[56:59]
	v_mfma_f32_16x16x32_bf16 v[44:47], v[100:103], v[194:197], v[44:47]
	v_mfma_f32_16x16x32_bf16 v[40:43], v[108:111], v[194:197], v[40:43]
	v_mfma_f32_16x16x32_bf16 v[28:31], v[100:103], v[202:205], v[28:31]
	v_mfma_f32_16x16x32_bf16 v[24:27], v[108:111], v[202:205], v[24:27]
	v_mfma_f32_16x16x32_bf16 v[12:15], v[100:103], v[212:215], v[12:15]
	v_mfma_f32_16x16x32_bf16 v[8:11], v[108:111], v[212:215], v[8:11]
	v_mfma_f32_16x16x32_bf16 v[52:55], v[156:159], v[172:175], v[52:55]
	v_mfma_f32_16x16x32_bf16 v[48:51], v[164:167], v[172:175], v[48:51]
	v_mfma_f32_16x16x32_bf16 v[36:39], v[156:159], v[190:193], v[36:39]
	v_mfma_f32_16x16x32_bf16 v[32:35], v[164:167], v[190:193], v[32:35]
	v_mfma_f32_16x16x32_bf16 v[20:23], v[156:159], v[198:201], v[20:23]
	v_mfma_f32_16x16x32_bf16 v[16:19], v[164:167], v[198:201], v[16:19]
	v_mfma_f32_16x16x32_bf16 v[4:7], v[156:159], v[206:209], v[4:7]
	v_mfma_f32_16x16x32_bf16 v[0:3], v[164:167], v[206:209], v[0:3]
	v_mfma_f32_16x16x32_bf16 v[52:55], v[160:163], v[176:179], v[52:55]
	v_mfma_f32_16x16x32_bf16 v[48:51], v[168:171], v[176:179], v[48:51]
	v_mfma_f32_16x16x32_bf16 v[36:39], v[160:163], v[194:197], v[36:39]
	v_mfma_f32_16x16x32_bf16 v[32:35], v[168:171], v[194:197], v[32:35]
	v_mfma_f32_16x16x32_bf16 v[20:23], v[160:163], v[202:205], v[20:23]
	v_mfma_f32_16x16x32_bf16 v[16:19], v[168:171], v[202:205], v[16:19]
	v_mfma_f32_16x16x32_bf16 v[4:7], v[160:163], v[212:215], v[4:7]
	v_mfma_f32_16x16x32_bf16 v[0:3], v[168:171], v[212:215], v[0:3]
	s_setprio 0
	s_barrier
	s_add_i32 s58, 0, 0x18000
	s_add_i32 s59, 0, 0x1c000
	v_add_u32_e32 v108, s58, v183
	v_add_u32_e32 v168, s59, v183
	ds_read_b128 v[96:99], v108
	ds_read_b128 v[100:103], v108 offset:1024
	ds_read_b128 v[104:107], v108 offset:2048
	ds_read_b128 v[108:111], v108 offset:3072
	ds_read_b128 v[156:159], v168
	ds_read_b128 v[160:163], v168 offset:1024
	ds_read_b128 v[164:167], v168 offset:2048
	ds_read_b128 v[168:171], v168 offset:3072
	v_lshl_add_u64 v[218:219], s[36:37], 0, v[144:145]
	s_mov_b32 m0, s15
	s_nop 0
	global_load_lds_dwordx4 v[218:219], off
	s_mov_b32 m0, s33
	s_nop 0
	global_load_lds_dwordx4 v[220:221], off
	s_add_u32 s26, s36, 0xb0000
	s_addc_u32 s27, s37, 0
	s_mov_b32 m0, s38
	v_lshl_add_u64 v[222:223], s[26:27], 0, v[144:145]
	ds_read_b128 v[172:175], v187 offset:32768
	ds_read_b128 v[176:179], v187 offset:33792
	ds_read_b128 v[190:193], v187 offset:34816
	ds_read_b128 v[194:197], v187 offset:35840
	ds_read_b128 v[198:201], v187 offset:36864
	ds_read_b128 v[202:205], v187 offset:37888
	ds_read_b128 v[206:209], v187 offset:38912
	ds_read_b128 v[212:215], v187 offset:39936
	global_load_lds_dwordx4 v[222:223], off
	v_lshl_add_u64 v[222:223], s[26:27], 0, v[146:147]
	s_mov_b32 m0, s39
	s_nop 0
	global_load_lds_dwordx4 v[222:223], off
	s_waitcnt vmcnt(8)
	s_waitcnt lgkmcnt(0)
	s_barrier
	s_setprio 1
	v_mfma_f32_16x16x32_bf16 v[140:143], v[96:99], v[172:175], v[140:143]
	v_mfma_f32_16x16x32_bf16 v[136:139], v[104:107], v[172:175], v[136:139]
	v_mfma_f32_16x16x32_bf16 v[124:127], v[96:99], v[190:193], v[124:127]
	v_mfma_f32_16x16x32_bf16 v[120:123], v[104:107], v[190:193], v[120:123]
	v_mfma_f32_16x16x32_bf16 v[92:95], v[96:99], v[198:201], v[92:95]
	v_mfma_f32_16x16x32_bf16 v[88:91], v[104:107], v[198:201], v[88:91]
	v_mfma_f32_16x16x32_bf16 v[76:79], v[96:99], v[206:209], v[76:79]
	v_mfma_f32_16x16x32_bf16 v[72:75], v[104:107], v[206:209], v[72:75]
	v_mfma_f32_16x16x32_bf16 v[140:143], v[100:103], v[176:179], v[140:143]
	v_mfma_f32_16x16x32_bf16 v[136:139], v[108:111], v[176:179], v[136:139]
	v_mfma_f32_16x16x32_bf16 v[124:127], v[100:103], v[194:197], v[124:127]
	v_mfma_f32_16x16x32_bf16 v[120:123], v[108:111], v[194:197], v[120:123]
	v_mfma_f32_16x16x32_bf16 v[92:95], v[100:103], v[202:205], v[92:95]
	v_mfma_f32_16x16x32_bf16 v[88:91], v[108:111], v[202:205], v[88:91]
	v_mfma_f32_16x16x32_bf16 v[76:79], v[100:103], v[212:215], v[76:79]
	v_mfma_f32_16x16x32_bf16 v[72:75], v[108:111], v[212:215], v[72:75]
	v_mfma_f32_16x16x32_bf16 v[132:135], v[156:159], v[172:175], v[132:135]
	v_mfma_f32_16x16x32_bf16 v[128:131], v[164:167], v[172:175], v[128:131]
	v_mfma_f32_16x16x32_bf16 v[116:119], v[156:159], v[190:193], v[116:119]
	v_mfma_f32_16x16x32_bf16 v[112:115], v[164:167], v[190:193], v[112:115]
	v_mfma_f32_16x16x32_bf16 v[84:87], v[156:159], v[198:201], v[84:87]
	v_mfma_f32_16x16x32_bf16 v[80:83], v[164:167], v[198:201], v[80:83]
	v_mfma_f32_16x16x32_bf16 v[68:71], v[156:159], v[206:209], v[68:71]
	v_mfma_f32_16x16x32_bf16 v[64:67], v[164:167], v[206:209], v[64:67]
	v_mfma_f32_16x16x32_bf16 v[132:135], v[160:163], v[176:179], v[132:135]
	v_mfma_f32_16x16x32_bf16 v[128:131], v[168:171], v[176:179], v[128:131]
	v_mfma_f32_16x16x32_bf16 v[116:119], v[160:163], v[194:197], v[116:119]
	v_mfma_f32_16x16x32_bf16 v[112:115], v[168:171], v[194:197], v[112:115]
	v_mfma_f32_16x16x32_bf16 v[84:87], v[160:163], v[202:205], v[84:87]
	v_mfma_f32_16x16x32_bf16 v[80:83], v[168:171], v[202:205], v[80:83]
	v_mfma_f32_16x16x32_bf16 v[68:71], v[160:163], v[212:215], v[68:71]
	v_mfma_f32_16x16x32_bf16 v[64:67], v[168:171], v[212:215], v[64:67]
	s_setprio 0
	s_barrier
	s_add_i32 s26, s58, s3
	v_lshl_add_u64 v[180:181], v[180:181], 0, s[16:17]
	s_mov_b32 m0, s26
	ds_read_b128 v[172:175], v187 offset:49152
	ds_read_b128 v[176:179], v187 offset:50176
	ds_read_b128 v[190:193], v187 offset:51200
	ds_read_b128 v[194:197], v187 offset:52224
	ds_read_b128 v[198:201], v187 offset:53248
	ds_read_b128 v[202:205], v187 offset:54272
	ds_read_b128 v[206:209], v187 offset:55296
	ds_read_b128 v[212:215], v187 offset:56320
	global_load_lds_dwordx4 v[180:181], off
	s_add_i32 m0, s26, 0x2000
	s_add_u32 s26, s34, 0xb0080
	v_lshl_add_u64 v[180:181], v[216:217], 0, s[16:17]
	s_addc_u32 s27, s35, 0
	s_add_i32 s34, s59, s3
	global_load_lds_dwordx4 v[180:181], off
	v_lshl_add_u64 v[180:181], s[26:27], 0, v[144:145]
	s_mov_b32 m0, s34
	s_nop 0
	global_load_lds_dwordx4 v[180:181], off
	v_lshl_add_u64 v[180:181], s[26:27], 0, v[146:147]
	s_add_i32 m0, s34, 0x2000
	s_nop 0
	global_load_lds_dwordx4 v[180:181], off
	v_lshl_add_u64 v[180:181], v[218:219], 0, s[16:17]
	s_mov_b32 m0, s45
	s_nop 0
	global_load_lds_dwordx4 v[180:181], off
	v_lshl_add_u64 v[180:181], v[220:221], 0, s[16:17]
	s_mov_b32 m0, s46
	s_nop 0
	global_load_lds_dwordx4 v[180:181], off
	s_waitcnt vmcnt(6)
	s_waitcnt lgkmcnt(0)
	s_barrier
	s_setprio 1
	v_mfma_f32_16x16x32_bf16 v[60:63], v[96:99], v[172:175], v[60:63]
	v_mfma_f32_16x16x32_bf16 v[56:59], v[104:107], v[172:175], v[56:59]
	v_mfma_f32_16x16x32_bf16 v[44:47], v[96:99], v[190:193], v[44:47]
	v_mfma_f32_16x16x32_bf16 v[40:43], v[104:107], v[190:193], v[40:43]
	v_mfma_f32_16x16x32_bf16 v[28:31], v[96:99], v[198:201], v[28:31]
	v_mfma_f32_16x16x32_bf16 v[24:27], v[104:107], v[198:201], v[24:27]
	v_mfma_f32_16x16x32_bf16 v[12:15], v[96:99], v[206:209], v[12:15]
	v_mfma_f32_16x16x32_bf16 v[8:11], v[104:107], v[206:209], v[8:11]
	v_mfma_f32_16x16x32_bf16 v[60:63], v[100:103], v[176:179], v[60:63]
	v_mfma_f32_16x16x32_bf16 v[56:59], v[108:111], v[176:179], v[56:59]
	v_mfma_f32_16x16x32_bf16 v[44:47], v[100:103], v[194:197], v[44:47]
	v_mfma_f32_16x16x32_bf16 v[40:43], v[108:111], v[194:197], v[40:43]
	v_mfma_f32_16x16x32_bf16 v[28:31], v[100:103], v[202:205], v[28:31]
	v_mfma_f32_16x16x32_bf16 v[24:27], v[108:111], v[202:205], v[24:27]
	v_mfma_f32_16x16x32_bf16 v[12:15], v[100:103], v[212:215], v[12:15]
	v_mfma_f32_16x16x32_bf16 v[8:11], v[108:111], v[212:215], v[8:11]
	v_mfma_f32_16x16x32_bf16 v[52:55], v[156:159], v[172:175], v[52:55]
	v_mfma_f32_16x16x32_bf16 v[48:51], v[164:167], v[172:175], v[48:51]
	v_mfma_f32_16x16x32_bf16 v[36:39], v[156:159], v[190:193], v[36:39]
	v_mfma_f32_16x16x32_bf16 v[32:35], v[164:167], v[190:193], v[32:35]
	v_mfma_f32_16x16x32_bf16 v[20:23], v[156:159], v[198:201], v[20:23]
	v_mfma_f32_16x16x32_bf16 v[16:19], v[164:167], v[198:201], v[16:19]
	v_mfma_f32_16x16x32_bf16 v[4:7], v[156:159], v[206:209], v[4:7]
	v_mfma_f32_16x16x32_bf16 v[0:3], v[164:167], v[206:209], v[0:3]
	v_mfma_f32_16x16x32_bf16 v[52:55], v[160:163], v[176:179], v[52:55]
	v_mfma_f32_16x16x32_bf16 v[48:51], v[168:171], v[176:179], v[48:51]
	v_mfma_f32_16x16x32_bf16 v[36:39], v[160:163], v[194:197], v[36:39]
	v_mfma_f32_16x16x32_bf16 v[32:35], v[168:171], v[194:197], v[32:35]
	v_mfma_f32_16x16x32_bf16 v[20:23], v[160:163], v[202:205], v[20:23]
	v_mfma_f32_16x16x32_bf16 v[16:19], v[168:171], v[202:205], v[16:19]
	v_mfma_f32_16x16x32_bf16 v[4:7], v[160:163], v[212:215], v[4:7]
	v_mfma_f32_16x16x32_bf16 v[0:3], v[168:171], v[212:215], v[0:3]
	s_setprio 0
	s_barrier
	s_add_i32 s57, s57, 2
	s_add_u32 s55, s55, 0x100
	s_addc_u32 s56, s56, 0
	s_cmp_gt_u32 s57, 41
	s_mov_b64 s[26:27], s[28:29]
	s_cbranch_scc0 .LBB0_722
	s_and_b64 vcc, exec, s[20:21]
	s_cbranch_vccz .LBB0_725
	s_barrier
